# combo14 + row-pass 1/2 LayerNorm butterflies: xor 1/2/4/8 steps via DPP (counted lgkmcnt waits behind converted steps made full waits)
# speedup vs baseline: 1.0160x; 1.0011x over previous
; #define LAS __attribute__((address_space(3)))
; __device__ __forceinline__ void wave_sum2(float& a, float& b) {
; #pragma unroll
;     for (int o = 1; o < 64; o <<= 1) { const float ta = __shfl_xor(a, o), tb = __shfl_xor(b, o); a += ta; b += tb; }
; }
; __device__ __forceinline__ void row_pass(const Params& P, int l, int mode, LAS float* pl) {
;     ...
;         if (mode != 0) {
;             float s[2], q[2];
; #pragma unroll
;             for (int r = 0; r < 2; ++r) { const LAS float* gm = pl + mv[r] * DM; s[r] = 0.f; q[r] = 0.f;
; #pragma unroll
;                 for (int j = 0; j < 4; ++j) { const f32x4 g = *(const LAS f32x4*)(gm + 4 * lane + 256 * j); v[r][j] = v[r][j] * ALPHA + g * yv[r][j];
;                     s[r] += (v[r][j][0] + v[r][j][1]) + (v[r][j][2] + v[r][j][3]); const f32x4 sq = v[r][j] * v[r][j]; q[r] += (sq[0] + sq[1]) + (sq[2] + sq[3]); } }
;             wave_sum2(s[0], s[1]); wave_sum2(q[0], q[1]);
.LBB0_1042:
	s_mul_i32 s4, s19, 0x2100
	s_add_i32 s10, s4, s10
	s_mul_i32 s4, s18, 0x2100
	s_add_i32 s14, s4, s14
	s_ashr_i32 s15, s14, 31
	s_ashr_i32 s11, s10, 31
	s_lshl_b64 s[4:5], s[14:15], 12
	s_lshl_b32 s18, s18, 12
	s_and_b64 s[0:1], s[0:1], exec
	s_cselect_b32 s0, s18, 0x2000
	v_add_u32_e32 v127, s0, v15
	ds_read_b128 v[128:131], v127
	ds_read_b128 v[140:143], v127 offset:1024
	s_mov_b32 s20, 0x3fd744fd
	s_lshl_b32 s18, s19, 12
	s_and_b64 s[0:1], exec, s[16:17]
	s_waitcnt lgkmcnt(1)
	v_pk_mul_f32 v[72:73], v[130:131], v[72:73]
	v_pk_mul_f32 v[70:71], v[128:129], v[70:71]
	v_pk_fma_f32 v[56:57], v[56:57], s[20:21], v[72:73] op_sel_hi:[1,0,1]
	v_pk_fma_f32 v[54:55], v[54:55], s[20:21], v[70:71] op_sel_hi:[1,0,1]
	v_pk_mul_f32 v[70:71], v[56:57], v[56:57]
	s_waitcnt lgkmcnt(0)
	v_pk_mul_f32 v[76:77], v[142:143], v[76:77]
	v_add_f32_e32 v0, v70, v71
	v_pk_mul_f32 v[70:71], v[140:141], v[74:75]
	v_pk_fma_f32 v[48:49], v[48:49], s[20:21], v[76:77] op_sel_hi:[1,0,1]
	v_pk_fma_f32 v[46:47], v[46:47], s[20:21], v[70:71] op_sel_hi:[1,0,1]
	ds_read_b128 v[70:73], v127 offset:2048
	ds_read_b128 v[74:77], v127 offset:3072
	v_pk_mul_f32 v[132:133], v[54:55], v[54:55]
	v_add_f32_e32 v129, v54, v55
	v_add_f32_e32 v131, v56, v57
	v_pk_mul_f32 v[142:143], v[46:47], v[46:47]
	s_waitcnt lgkmcnt(1)
	v_pk_mul_f32 v[72:73], v[72:73], v[84:85]
	v_pk_mul_f32 v[70:71], v[70:71], v[82:83]
	v_mov_b32_e32 v128, v132
	v_mov_b32_e32 v130, v133
	v_pk_mul_f32 v[140:141], v[48:49], v[48:49]
	v_pk_fma_f32 v[42:43], v[42:43], s[20:21], v[70:71] op_sel_hi:[1,0,1]
	v_pk_fma_f32 v[44:45], v[44:45], s[20:21], v[72:73] op_sel_hi:[1,0,1]
	s_waitcnt lgkmcnt(0)
	v_pk_mul_f32 v[70:71], v[76:77], v[80:81]
	v_pk_mul_f32 v[72:73], v[74:75], v[78:79]
	v_pk_add_f32 v[78:79], v[128:129], v[130:131]
	v_mov_b32_e32 v80, v142
	v_mov_b32_e32 v81, v46
	v_mov_b32_e32 v128, v143
	v_mov_b32_e32 v129, v47
	v_pk_add_f32 v[80:81], v[80:81], v[128:129]
	v_mov_b32_e32 v128, v140
	v_mov_b32_e32 v129, v48
	v_mov_b32_e32 v130, v141
	v_mov_b32_e32 v131, v49
	v_pk_add_f32 v[128:129], v[128:129], v[130:131]
	v_pk_mul_f32 v[84:85], v[42:43], v[42:43]
	v_pk_add_f32 v[78:79], v[78:79], v[0:1]
	v_pk_add_f32 v[80:81], v[80:81], v[128:129]
	v_pk_mul_f32 v[82:83], v[44:45], v[44:45]
	v_pk_add_f32 v[78:79], v[78:79], v[80:81]
	v_mov_b32_e32 v80, v84
	v_mov_b32_e32 v81, v42
	v_mov_b32_e32 v84, v85
	v_mov_b32_e32 v85, v43
	v_pk_add_f32 v[80:81], v[80:81], v[84:85]
	v_mov_b32_e32 v84, v82
	v_mov_b32_e32 v85, v44
	v_mov_b32_e32 v82, v83
	v_mov_b32_e32 v83, v45
	v_pk_fma_f32 v[38:39], v[38:39], s[20:21], v[72:73] op_sel_hi:[1,0,1]
	v_pk_add_f32 v[82:83], v[84:85], v[82:83]
	v_pk_fma_f32 v[40:41], v[40:41], s[20:21], v[70:71] op_sel_hi:[1,0,1]
	v_pk_mul_f32 v[76:77], v[38:39], v[38:39]
	v_pk_add_f32 v[80:81], v[80:81], v[82:83]
	v_pk_mul_f32 v[74:75], v[40:41], v[40:41]
	v_pk_add_f32 v[78:79], v[78:79], v[80:81]
	v_mov_b32_e32 v80, v76
	v_mov_b32_e32 v81, v38
	v_mov_b32_e32 v76, v77
	v_mov_b32_e32 v77, v39
	v_pk_add_f32 v[76:77], v[80:81], v[76:77]
	v_mov_b32_e32 v80, v74
	v_mov_b32_e32 v81, v40
	v_mov_b32_e32 v74, v75
	v_mov_b32_e32 v75, v41
	s_cselect_b32 s0, s18, 0x2000
	v_pk_add_f32 v[74:75], v[80:81], v[74:75]
	v_add_u32_e32 v126, s0, v15
	v_pk_add_f32 v[74:75], v[76:77], v[74:75]
	ds_read_b128 v[70:73], v126
	v_pk_add_f32 v[78:79], v[78:79], v[74:75]
	s_nop 1
	v_mov_b32_dpp v81, v79 quad_perm:[1,0,3,2] row_mask:0xf bank_mask:0xf
	s_nop 1
	v_mov_b32_dpp v80, v78 quad_perm:[1,0,3,2] row_mask:0xf bank_mask:0xf
	ds_read_b128 v[74:77], v126 offset:1024
	s_waitcnt lgkmcnt(0)
	v_pk_mul_f32 v[72:73], v[72:73], v[88:89]
	v_pk_mul_f32 v[82:83], v[70:71], v[86:87]
	v_pk_fma_f32 v[70:71], v[68:69], s[20:21], v[72:73] op_sel_hi:[1,0,1]
	s_waitcnt lgkmcnt(0)
	v_pk_add_f32 v[68:69], v[78:79], v[80:81]
	s_nop 1
	v_mov_b32_dpp v79, v69 quad_perm:[2,3,0,1] row_mask:0xf bank_mask:0xf
	s_nop 1
	v_mov_b32_dpp v78, v68 quad_perm:[2,3,0,1] row_mask:0xf bank_mask:0xf
	v_pk_fma_f32 v[72:73], v[66:67], s[20:21], v[82:83] op_sel_hi:[1,0,1]
	s_waitcnt lgkmcnt(0)
	v_pk_mul_f32 v[76:77], v[76:77], v[92:93]
	v_pk_mul_f32 v[74:75], v[74:75], v[90:91]
	s_mov_b32 s16, 0x3a800000
	s_waitcnt lgkmcnt(0)
	v_pk_add_f32 v[66:67], v[68:69], v[78:79]
	s_nop 1
	v_mov_b32_dpp v69, v67 row_half_mirror row_mask:0xf bank_mask:0xf
	s_nop 1
	v_mov_b32_dpp v68, v66 row_half_mirror row_mask:0xf bank_mask:0xf
	v_pk_mul_f32 v[78:79], v[70:71], v[70:71]
	v_pk_fma_f32 v[74:75], v[62:63], s[20:21], v[74:75] op_sel_hi:[1,0,1]
	v_add_f32_e32 v140, v78, v79
	v_pk_fma_f32 v[78:79], v[64:65], s[20:21], v[76:77] op_sel_hi:[1,0,1]
	s_waitcnt lgkmcnt(0)
	v_pk_add_f32 v[66:67], v[66:67], v[68:69]
	s_nop 1
	v_mov_b32_dpp v69, v67 row_mirror row_mask:0xf bank_mask:0xf
	s_nop 1
	v_mov_b32_dpp v68, v66 row_mirror row_mask:0xf bank_mask:0xf
	ds_read_b128 v[62:65], v126 offset:2048
	v_pk_mul_f32 v[132:133], v[72:73], v[72:73]
	v_pk_mul_f32 v[144:145], v[74:75], v[74:75]
	v_add_f32_e32 v129, v72, v73
	s_waitcnt lgkmcnt(0)
	v_pk_add_f32 v[76:77], v[66:67], v[68:69]
	ds_bpermute_b32 v81, v137, v77
	ds_bpermute_b32 v80, v137, v76
	ds_read_b128 v[66:69], v126 offset:3072
	s_waitcnt lgkmcnt(0)
	v_pk_mul_f32 v[62:63], v[62:63], v[98:99]
	v_add_f32_e32 v131, v70, v71
	v_pk_mul_f32 v[142:143], v[78:79], v[78:79]
	s_waitcnt lgkmcnt(0)
	v_pk_add_f32 v[82:83], v[76:77], v[80:81]
	ds_bpermute_b32 v85, v138, v83
	ds_bpermute_b32 v84, v138, v82
	v_pk_fma_f32 v[76:77], v[58:59], s[20:21], v[62:63] op_sel_hi:[1,0,1]
	s_waitcnt lgkmcnt(0)
	v_pk_mul_f32 v[66:67], v[66:67], v[94:95]
	v_pk_mul_f32 v[64:65], v[64:65], v[100:101]
	v_mov_b32_e32 v128, v132
	s_waitcnt lgkmcnt(0)
; #define LAS __attribute__((address_space(3)))
; __device__ __forceinline__ void row_pass(const Params& P, int l, int mode, LAS float* pl) {
;     ...
;             wave_sum2(s[0], s[1]); wave_sum2(q[0], q[1]);
; #pragma unroll
;             for (int r = 0; r < 2; ++r) { const float mean = s[r] * (1.f / DM); const float var = fmaxf(q[r] * (1.f / DM) - mean * mean, 0.f); const float rstd = 1.f / sqrtf(var + LN_EPS);
; #pragma unroll
;                 for (int j = 0; j < 4; ++j) { const f32x4 g = *(const LAS f32x4*)(pl + 3072 + 4 * lane + 256 * j), bb = *(const LAS f32x4*)(pl + 4096 + 4 * lane + 256 * j); v[r][j] = (v[r][j] - mean) * rstd * g + bb; } }
	v_pk_add_f32 v[62:63], v[82:83], v[84:85]
	v_pk_fma_f32 v[82:83], v[50:51], s[20:21], v[66:67] op_sel_hi:[1,0,1]
	v_pk_mul_f32 v[62:63], v[62:63], s[16:17] op_sel_hi:[1,0]
	s_mov_b32 s17, 0xf800000
	v_fma_f32 v0, -v63, v63, v62
	v_max_f32_e32 v0, 0, v0
	v_add_f32_e32 v0, 0x358637bd, v0
	v_mul_f32_e32 v62, 0x4f800000, v0
	v_cmp_gt_f32_e32 vcc, s17, v0
	v_mov_b32_e32 v130, v133
	v_mov_b32_e32 v98, v144
	v_cndmask_b32_e32 v0, v0, v62, vcc
	v_sqrt_f32_e32 v62, v0
	v_mov_b32_e32 v99, v74
	v_mov_b32_e32 v100, v145
	v_mov_b32_e32 v101, v75
	v_add_u32_e32 v50, -1, v62
	v_fma_f32 v51, -v50, v62, v0
	v_cmp_ge_f32_e64 s[0:1], 0, v51
	v_add_u32_e32 v51, 1, v62
	v_pk_fma_f32 v[80:81], v[60:61], s[20:21], v[64:65] op_sel_hi:[1,0,1]
	v_cndmask_b32_e64 v50, v62, v50, s[0:1]
	v_fma_f32 v62, -v51, v62, v0
	v_cmp_lt_f32_e64 s[0:1], 0, v62
	v_pk_mul_f32 v[64:65], v[68:69], v[96:97]
	v_pk_add_f32 v[68:69], v[128:129], v[130:131]
	v_cndmask_b32_e64 v50, v50, v51, s[0:1]
	v_mul_f32_e32 v51, 0x37800000, v50
	v_cndmask_b32_e32 v50, v50, v51, vcc
	v_cmp_class_f32_e32 vcc, v0, v217
	v_pk_add_f32 v[98:99], v[98:99], v[100:101]
	v_mov_b32_e32 v100, v142
	v_cndmask_b32_e32 v0, v50, v0, vcc
	v_div_scale_f32 v50, s[0:1], v0, v0, 1.0
	v_rcp_f32_e32 v51, v50
	v_mov_b32_e32 v101, v78
	v_mov_b32_e32 v128, v143
	v_mov_b32_e32 v129, v79
	v_mov_b32_e32 v141, v1
	v_pk_add_f32 v[100:101], v[100:101], v[128:129]
	v_pk_mul_f32 v[60:61], v[76:77], v[76:77]
	v_pk_add_f32 v[68:69], v[68:69], v[140:141]
	v_pk_add_f32 v[98:99], v[98:99], v[100:101]
	v_pk_mul_f32 v[58:59], v[80:81], v[80:81]
	v_pk_add_f32 v[68:69], v[68:69], v[98:99]
	v_mov_b32_e32 v98, v60
	v_mov_b32_e32 v99, v76
	v_mov_b32_e32 v60, v61
	v_mov_b32_e32 v61, v77
	v_pk_fma_f32 v[84:85], v[52:53], s[20:21], v[64:65] op_sel_hi:[1,0,1]
	v_fma_f32 v52, -v50, v51, 1.0
	v_pk_add_f32 v[60:61], v[98:99], v[60:61]
	v_mov_b32_e32 v98, v58
	v_mov_b32_e32 v99, v80
	v_mov_b32_e32 v58, v59
	v_mov_b32_e32 v59, v81
	v_pk_mul_f32 v[66:67], v[82:83], v[82:83]
	v_fmac_f32_e32 v51, v52, v51
	v_div_scale_f32 v52, vcc, 1.0, v0, 1.0
	v_pk_add_f32 v[58:59], v[98:99], v[58:59]
	v_pk_mul_f32 v[64:65], v[84:85], v[84:85]
	v_mul_f32_e32 v53, v52, v51
	v_pk_add_f32 v[58:59], v[60:61], v[58:59]
	v_mov_b32_e32 v60, v66
	v_mov_b32_e32 v61, v82
	v_mov_b32_e32 v66, v67
	v_mov_b32_e32 v67, v83
	v_fma_f32 v62, -v50, v53, v52
	v_pk_add_f32 v[60:61], v[60:61], v[66:67]
	v_mov_b32_e32 v66, v64
	v_mov_b32_e32 v67, v84
	v_mov_b32_e32 v64, v65
	v_mov_b32_e32 v65, v85
	v_fmac_f32_e32 v53, v62, v51
	v_pk_add_f32 v[64:65], v[66:67], v[64:65]
	v_fma_f32 v50, -v50, v53, v52
	v_pk_add_f32 v[58:59], v[68:69], v[58:59]
	v_pk_add_f32 v[60:61], v[60:61], v[64:65]
	v_div_fmas_f32 v50, v50, v51, v53
	v_pk_add_f32 v[58:59], v[58:59], v[60:61]
	v_div_fixup_f32 v0, v50, v0, 1.0
	v_sub_f32_e32 v51, v57, v63
	v_sub_f32_e32 v50, v56, v63
	v_sub_f32_e32 v53, v55, v63
	v_sub_f32_e32 v52, v54, v63
	s_nop 1
	v_mov_b32_dpp v61, v59 quad_perm:[1,0,3,2] row_mask:0xf bank_mask:0xf
	s_nop 1
	v_mov_b32_dpp v60, v58 quad_perm:[1,0,3,2] row_mask:0xf bank_mask:0xf
	v_pk_mul_f32 v[54:55], v[52:53], v[0:1] op_sel_hi:[1,0]
	v_pk_mul_f32 v[56:57], v[50:51], v[0:1] op_sel_hi:[1,0]
	ds_read_b128 v[50:53], v15 offset:12288
	ds_read_b128 v[86:89], v15 offset:13312
	ds_read_b128 v[90:93], v15 offset:16384
	ds_read_b128 v[94:97], v15 offset:17408
	v_sub_f32_e32 v47, v47, v63
	v_sub_f32_e32 v46, v46, v63
	v_sub_f32_e32 v49, v49, v63
	s_waitcnt lgkmcnt(0)
	v_pk_fma_f32 v[66:67], v[50:51], v[54:55], v[90:91]
	v_pk_add_f32 v[54:55], v[58:59], v[60:61]
	v_pk_fma_f32 v[68:69], v[52:53], v[56:57], v[92:93]
	s_nop 1
	v_mov_b32_dpp v57, v55 quad_perm:[2,3,0,1] row_mask:0xf bank_mask:0xf
	s_nop 1
	v_mov_b32_dpp v56, v54 quad_perm:[2,3,0,1] row_mask:0xf bank_mask:0xf
	v_sub_f32_e32 v48, v48, v63
	v_pk_mul_f32 v[46:47], v[46:47], v[0:1] op_sel_hi:[1,0]
	v_pk_mul_f32 v[48:49], v[48:49], v[0:1] op_sel_hi:[1,0]
	s_waitcnt lgkmcnt(0)
	v_pk_fma_f32 v[58:59], v[86:87], v[46:47], v[94:95]
	s_waitcnt lgkmcnt(0)
	v_pk_add_f32 v[54:55], v[54:55], v[56:57]
	s_nop 1
	v_mov_b32_dpp v57, v55 row_half_mirror row_mask:0xf bank_mask:0xf
	s_nop 1
	v_mov_b32_dpp v56, v54 row_half_mirror row_mask:0xf bank_mask:0xf
	v_pk_fma_f32 v[60:61], v[88:89], v[48:49], v[96:97]
	v_sub_f32_e32 v45, v45, v63
	v_sub_f32_e32 v44, v44, v63
	v_sub_f32_e32 v43, v43, v63
	s_waitcnt lgkmcnt(0)
	v_pk_add_f32 v[46:47], v[54:55], v[56:57]
	s_nop 1
	v_mov_b32_dpp v49, v47 row_mirror row_mask:0xf bank_mask:0xf
	s_nop 1
	v_mov_b32_dpp v48, v46 row_mirror row_mask:0xf bank_mask:0xf
	v_sub_f32_e32 v42, v42, v63
	v_pk_mul_f32 v[54:55], v[42:43], v[0:1] op_sel_hi:[1,0]
	v_pk_mul_f32 v[56:57], v[44:45], v[0:1] op_sel_hi:[1,0]
	ds_read_b128 v[42:45], v15 offset:14336
	ds_read_b128 v[98:101], v15 offset:15360
	ds_read_b128 v[128:131], v15 offset:18432
	ds_read_b128 v[140:143], v15 offset:19456
	s_waitcnt lgkmcnt(0)
	v_pk_add_f32 v[46:47], v[46:47], v[48:49]
	ds_bpermute_b32 v49, v137, v47
	ds_bpermute_b32 v48, v137, v46
	v_sub_f32_e32 v41, v41, v63
	v_sub_f32_e32 v40, v40, v63
	v_sub_f32_e32 v39, v39, v63
	v_sub_f32_e32 v38, v38, v63
	s_waitcnt lgkmcnt(0)
	v_pk_add_f32 v[46:47], v[46:47], v[48:49]
	ds_bpermute_b32 v49, v138, v47
	ds_bpermute_b32 v48, v138, v46
	v_pk_mul_f32 v[38:39], v[38:39], v[0:1] op_sel_hi:[1,0]
	v_pk_mul_f32 v[40:41], v[40:41], v[0:1] op_sel_hi:[1,0]
	v_pk_fma_f32 v[62:63], v[98:99], v[38:39], v[140:141]
	v_pk_fma_f32 v[64:65], v[100:101], v[40:41], v[142:143]
	s_waitcnt lgkmcnt(0)
; #define LAS __attribute__((address_space(3)))
; __device__ __forceinline__ void row_pass(const Params& P, int l, int mode, LAS float* pl) {
;     ...
;             for (int r = 0; r < 2; ++r) { const float mean = s[r] * (1.f / DM); const float var = fmaxf(q[r] * (1.f / DM) - mean * mean, 0.f); const float rstd = 1.f / sqrtf(var + LN_EPS);
; #pragma unroll
;                 for (int j = 0; j < 4; ++j) { const f32x4 g = *(const LAS f32x4*)(pl + 3072 + 4 * lane + 256 * j), bb = *(const LAS f32x4*)(pl + 4096 + 4 * lane + 256 * j); v[r][j] = (v[r][j] - mean) * rstd * g + bb; } }
;         }
;         if (mode != 0) {
; #pragma unroll
;         for (int r = 0; r < 2; ++r) if (ok[r]) {
; #pragma unroll
;             for (int j = 0; j < 4; ++j) __builtin_nontemporal_store(v[r][j], (f32x4*)(dst[r] + 4 * lane + 256 * j)); } }
;         if (make_h) {
;             float s[2], q[2];
; #pragma unroll
;             for (int r = 0; r < 2; ++r) { s[r] = 0.f; q[r] = 0.f;
; #pragma unroll
;                 for (int j = 0; j < 4; ++j) { s[r] += (v[r][j][0] + v[r][j][1]) + (v[r][j][2] + v[r][j][3]); const f32x4 sq = v[r][j] * v[r][j]; q[r] += (sq[0] + sq[1]) + (sq[2] + sq[3]); } }
;             wave_sum2(s[0], s[1]); wave_sum2(q[0], q[1]);
	v_pk_add_f32 v[46:47], v[46:47], v[48:49]
	v_pk_fma_f32 v[56:57], v[44:45], v[56:57], v[130:131]
	v_pk_mul_f32 v[132:133], v[46:47], s[16:17] op_sel_hi:[1,0]
	v_pk_fma_f32 v[54:55], v[42:43], v[54:55], v[128:129]
	v_fma_f32 v46, -v133, v133, v132
	v_max_f32_e32 v46, 0, v46
	v_add_f32_e32 v46, 0x358637bd, v46
	v_mul_f32_e32 v47, 0x4f800000, v46
	v_cmp_gt_f32_e32 vcc, s17, v46
	v_sub_f32_e32 v41, v73, v133
	v_sub_f32_e32 v40, v72, v133
	v_cndmask_b32_e32 v46, v46, v47, vcc
	v_sqrt_f32_e32 v47, v46
	s_mov_b32 s18, 0x3a800000
	s_mov_b32 s16, 0xf800000
	v_add_u32_e32 v48, -1, v47
	v_fma_f32 v49, -v48, v47, v46
	v_cmp_ge_f32_e64 s[0:1], 0, v49
	v_add_u32_e32 v49, 1, v47
	s_nop 0
	v_cndmask_b32_e64 v48, v47, v48, s[0:1]
	v_fma_f32 v47, -v49, v47, v46
	v_cmp_lt_f32_e64 s[0:1], 0, v47
	s_nop 1
	v_cndmask_b32_e64 v47, v48, v49, s[0:1]
	v_mul_f32_e32 v48, 0x37800000, v47
	v_cndmask_b32_e32 v47, v47, v48, vcc
	v_cmp_class_f32_e32 vcc, v46, v217
	s_nop 1
	v_cndmask_b32_e32 v46, v47, v46, vcc
	v_div_scale_f32 v47, s[0:1], v46, v46, 1.0
	v_rcp_f32_e32 v48, v47
	s_nop 0
	v_fma_f32 v0, -v47, v48, 1.0
	v_fmac_f32_e32 v48, v0, v48
	v_div_scale_f32 v0, vcc, 1.0, v46, 1.0
	v_mul_f32_e32 v38, v0, v48
	v_fma_f32 v39, -v47, v38, v0
	v_fmac_f32_e32 v38, v39, v48
	v_fma_f32 v0, -v47, v38, v0
	v_div_fmas_f32 v0, v0, v48, v38
	v_div_fixup_f32 v0, v0, v46, 1.0
	v_sub_f32_e32 v39, v71, v133
	v_sub_f32_e32 v38, v70, v133
	v_pk_mul_f32 v[40:41], v[40:41], v[0:1] op_sel_hi:[1,0]
	v_pk_mul_f32 v[38:39], v[38:39], v[0:1] op_sel_hi:[1,0]
	v_pk_fma_f32 v[50:51], v[50:51], v[40:41], v[90:91]
	v_pk_fma_f32 v[52:53], v[52:53], v[38:39], v[92:93]
	v_sub_f32_e32 v39, v79, v133
	v_sub_f32_e32 v38, v78, v133
	v_sub_f32_e32 v41, v75, v133
	v_sub_f32_e32 v40, v74, v133
	v_pk_mul_f32 v[40:41], v[40:41], v[0:1] op_sel_hi:[1,0]
	v_pk_mul_f32 v[38:39], v[38:39], v[0:1] op_sel_hi:[1,0]
	v_pk_fma_f32 v[46:47], v[86:87], v[40:41], v[94:95]
	v_pk_fma_f32 v[48:49], v[88:89], v[38:39], v[96:97]
	v_sub_f32_e32 v39, v81, v133
	v_sub_f32_e32 v38, v80, v133
	v_sub_f32_e32 v41, v77, v133
	v_sub_f32_e32 v40, v76, v133
	v_pk_mul_f32 v[40:41], v[40:41], v[0:1] op_sel_hi:[1,0]
	v_pk_mul_f32 v[38:39], v[38:39], v[0:1] op_sel_hi:[1,0]
	v_pk_fma_f32 v[42:43], v[42:43], v[40:41], v[128:129]
	v_pk_fma_f32 v[44:45], v[44:45], v[38:39], v[130:131]
	v_sub_f32_e32 v39, v85, v133
	v_sub_f32_e32 v38, v84, v133
	v_sub_f32_e32 v41, v83, v133
	v_sub_f32_e32 v40, v82, v133
	v_pk_mul_f32 v[70:71], v[40:41], v[0:1] op_sel_hi:[1,0]
	v_pk_mul_f32 v[38:39], v[38:39], v[0:1] op_sel_hi:[1,0]
	v_cndmask_b32_e64 v0, 0, 1, s[12:13]
	v_pk_fma_f32 v[40:41], v[100:101], v[38:39], v[142:143]
	v_pk_fma_f32 v[38:39], v[98:99], v[70:71], v[140:141]
	v_lshl_add_u64 v[70:71], v[108:109], 0, s[4:5]
	v_cmp_ne_u32_e64 s[4:5], 1, v0
	s_andn2_b64 vcc, exec, s[12:13]
	global_store_dwordx4 v[70:71], v[66:69], off nt
	global_store_dwordx4 v[70:71], v[58:61], off offset:1024 nt
	global_store_dwordx4 v[70:71], v[54:57], off offset:2048 nt
	global_store_dwordx4 v[70:71], v[62:65], off offset:3072 nt
	s_cbranch_vccnz .LBB0_1044
	s_lshl_b64 s[0:1], s[10:11], 12
	v_lshl_add_u64 v[70:71], v[108:109], 0, s[0:1]
	global_store_dwordx4 v[70:71], v[50:53], off nt
	global_store_dwordx4 v[70:71], v[46:49], off offset:1024 nt
	global_store_dwordx4 v[70:71], v[42:45], off offset:2048 nt
	global_store_dwordx4 v[70:71], v[38:41], off offset:3072 nt
.LBB0_1044:
	v_pk_mul_f32 v[96:97], v[50:51], v[50:51]
	v_pk_mul_f32 v[94:95], v[52:53], v[52:53]
	v_pk_mul_f32 v[100:101], v[46:47], v[46:47]
	v_mov_b32_e32 v140, v96
	v_mov_b32_e32 v141, v46
	v_mov_b32_e32 v96, v97
	v_mov_b32_e32 v97, v47
	v_add_f32_e32 v91, v50, v51
	v_add_f32_e32 v93, v52, v53
	v_pk_mul_f32 v[98:99], v[48:49], v[48:49]
	v_pk_add_f32 v[96:97], v[140:141], v[96:97]
	v_mov_b32_e32 v140, v94
	v_mov_b32_e32 v141, v48
	v_mov_b32_e32 v94, v95
	v_mov_b32_e32 v95, v49
	v_mov_b32_e32 v90, v100
	v_mov_b32_e32 v92, v101
	v_add_f32_e32 v0, v98, v99
	v_pk_add_f32 v[94:95], v[140:141], v[94:95]
	v_pk_add_f32 v[90:91], v[90:91], v[92:93]
	v_pk_mul_f32 v[128:129], v[42:43], v[42:43]
	v_pk_add_f32 v[94:95], v[96:97], v[94:95]
	v_pk_add_f32 v[90:91], v[90:91], v[0:1]
	v_pk_mul_f32 v[98:99], v[44:45], v[44:45]
	v_pk_add_f32 v[90:91], v[94:95], v[90:91]
	v_mov_b32_e32 v92, v128
	v_mov_b32_e32 v93, v42
	v_mov_b32_e32 v94, v129
	v_mov_b32_e32 v95, v43
	v_pk_add_f32 v[92:93], v[92:93], v[94:95]
	v_mov_b32_e32 v94, v98
	v_mov_b32_e32 v95, v44
	v_mov_b32_e32 v96, v99
	v_mov_b32_e32 v97, v45
	v_pk_mul_f32 v[76:77], v[66:67], v[66:67]
	v_pk_add_f32 v[94:95], v[94:95], v[96:97]
	v_pk_mul_f32 v[74:75], v[68:69], v[68:69]
	v_pk_mul_f32 v[80:81], v[58:59], v[58:59]
	v_pk_add_f32 v[92:93], v[92:93], v[94:95]
	v_mov_b32_e32 v94, v76
	v_mov_b32_e32 v95, v58
	v_mov_b32_e32 v76, v77
	v_mov_b32_e32 v77, v59
	v_add_f32_e32 v71, v66, v67
	v_add_f32_e32 v73, v68, v69
	v_pk_mul_f32 v[78:79], v[60:61], v[60:61]
	v_pk_add_f32 v[76:77], v[94:95], v[76:77]
	v_mov_b32_e32 v94, v74
	v_mov_b32_e32 v95, v60
	v_mov_b32_e32 v74, v75
	v_mov_b32_e32 v75, v61
	v_mov_b32_e32 v70, v80
	v_mov_b32_e32 v72, v81
	v_add_f32_e32 v78, v78, v79
	v_pk_add_f32 v[74:75], v[94:95], v[74:75]
	v_pk_add_f32 v[70:71], v[70:71], v[72:73]
	v_mov_b32_e32 v79, v1
	v_pk_mul_f32 v[84:85], v[54:55], v[54:55]
	v_pk_add_f32 v[74:75], v[76:77], v[74:75]
	v_pk_add_f32 v[70:71], v[70:71], v[78:79]
	v_pk_mul_f32 v[82:83], v[56:57], v[56:57]
	v_pk_add_f32 v[70:71], v[74:75], v[70:71]
	v_mov_b32_e32 v72, v84
	v_mov_b32_e32 v73, v54
	v_mov_b32_e32 v74, v85
	v_mov_b32_e32 v75, v55
	v_pk_add_f32 v[72:73], v[72:73], v[74:75]
	v_mov_b32_e32 v74, v82
	v_mov_b32_e32 v75, v56
	v_mov_b32_e32 v76, v83
	v_mov_b32_e32 v77, v57
	v_pk_add_f32 v[74:75], v[74:75], v[76:77]
	v_pk_mul_f32 v[88:89], v[62:63], v[62:63]
	v_pk_add_f32 v[72:73], v[72:73], v[74:75]
	v_pk_mul_f32 v[86:87], v[64:65], v[64:65]
	v_pk_add_f32 v[70:71], v[72:73], v[70:71]
	v_mov_b32_e32 v72, v88
	v_mov_b32_e32 v73, v62
	v_mov_b32_e32 v74, v89
	v_mov_b32_e32 v75, v63
	v_pk_add_f32 v[72:73], v[72:73], v[74:75]
	v_mov_b32_e32 v74, v86
	v_mov_b32_e32 v75, v64
	v_mov_b32_e32 v76, v87
	v_mov_b32_e32 v77, v65
	v_pk_add_f32 v[74:75], v[74:75], v[76:77]
	v_pk_mul_f32 v[130:131], v[40:41], v[40:41]
	v_pk_add_f32 v[72:73], v[72:73], v[74:75]
	v_pk_mul_f32 v[132:133], v[38:39], v[38:39]
	v_pk_add_f32 v[70:71], v[72:73], v[70:71]
	s_nop 1
	v_mov_b32_dpp v73, v71 quad_perm:[1,0,3,2] row_mask:0xf bank_mask:0xf
	s_nop 1
	v_mov_b32_dpp v72, v70 quad_perm:[1,0,3,2] row_mask:0xf bank_mask:0xf
	v_pk_add_f32 v[90:91], v[92:93], v[90:91]
	v_mov_b32_e32 v92, v132
	v_mov_b32_e32 v93, v38
	v_mov_b32_e32 v74, v133
	s_waitcnt lgkmcnt(0)
; #define LAS __attribute__((address_space(3)))
; __device__ __forceinline__ unsigned cvt_pk_bf16(float lo, float hi) { unsigned r; asm volatile("v_cvt_pk_bf16_f32 %0, %1, %2" : "=v"(r) : "v"(lo), "v"(hi)); return r; }
; __device__ __forceinline__ void row_pass(const Params& P, int l, int mode, LAS float* pl) {
;     ...
;             wave_sum2(s[0], s[1]); wave_sum2(q[0], q[1]);
; #pragma unroll
;             for (int r = 0; r < 2; ++r) if (ok[r]) { const float mean = s[r] * (1.f / DM); const float var = fmaxf(q[r] * (1.f / DM) - mean * mean, 0.f); const float rstd = 1.f / sqrtf(var + LN_EPS);
;                 const LAS float* mm = pl + 5120 + mv[r] * DM;
; #pragma unroll
;                 for (int j = 0; j < 4; ++j) { const f32x4 sh = *(const LAS f32x4*)(mm + 4 * lane + 256 * j), sc1 = *(const LAS f32x4*)(mm + 3072 + 4 * lane + 256 * j);
;                     const f32x4 hv = (v[r][j] - mean) * rstd * sc1 + sh; u32x2 o; o.x = cvt_pk_bf16(hv[0], hv[1]); o.y = cvt_pk_bf16(hv[2], hv[3]);
;                     *(u32x2*)(H + (size_t)row[r] * DM + 4 * lane + 256 * j) = o; } }
	v_pk_add_f32 v[70:71], v[70:71], v[72:73]
	s_nop 1
	v_mov_b32_dpp v73, v71 quad_perm:[2,3,0,1] row_mask:0xf bank_mask:0xf
	s_nop 1
	v_mov_b32_dpp v72, v70 quad_perm:[2,3,0,1] row_mask:0xf bank_mask:0xf
	v_mov_b32_e32 v75, v39
	v_mov_b32_e32 v76, v130
	v_mov_b32_e32 v77, v40
	v_mov_b32_e32 v78, v131
	s_waitcnt lgkmcnt(0)
	v_pk_add_f32 v[70:71], v[70:71], v[72:73]
	s_nop 1
	v_mov_b32_dpp v73, v71 row_half_mirror row_mask:0xf bank_mask:0xf
	s_nop 1
	v_mov_b32_dpp v72, v70 row_half_mirror row_mask:0xf bank_mask:0xf
	v_mov_b32_e32 v79, v41
	v_pk_add_f32 v[74:75], v[92:93], v[74:75]
	v_pk_add_f32 v[76:77], v[76:77], v[78:79]
	s_waitcnt lgkmcnt(0)
	v_pk_add_f32 v[70:71], v[70:71], v[72:73]
	s_nop 1
	v_mov_b32_dpp v73, v71 row_mirror row_mask:0xf bank_mask:0xf
	s_nop 1
	v_mov_b32_dpp v72, v70 row_mirror row_mask:0xf bank_mask:0xf
	v_pk_add_f32 v[74:75], v[74:75], v[76:77]
	s_waitcnt lgkmcnt(0)
	v_pk_add_f32 v[70:71], v[70:71], v[72:73]
	v_pk_add_f32 v[74:75], v[74:75], v[90:91]
	s_nop 1
	v_mov_b32_dpp v77, v75 quad_perm:[1,0,3,2] row_mask:0xf bank_mask:0xf
	s_nop 1
	v_mov_b32_dpp v76, v74 quad_perm:[1,0,3,2] row_mask:0xf bank_mask:0xf
	ds_bpermute_b32 v73, v137, v71
	ds_bpermute_b32 v72, v137, v70
	s_waitcnt lgkmcnt(0)
	v_pk_add_f32 v[74:75], v[74:75], v[76:77]
	s_nop 1
	v_mov_b32_dpp v77, v75 quad_perm:[2,3,0,1] row_mask:0xf bank_mask:0xf
	s_nop 1
	v_mov_b32_dpp v76, v74 quad_perm:[2,3,0,1] row_mask:0xf bank_mask:0xf
	s_waitcnt lgkmcnt(0)
	v_pk_add_f32 v[70:71], v[70:71], v[72:73]
	ds_bpermute_b32 v73, v138, v71
	ds_bpermute_b32 v72, v138, v70
	s_waitcnt lgkmcnt(0)
	v_pk_add_f32 v[74:75], v[74:75], v[76:77]
	s_nop 1
	v_mov_b32_dpp v77, v75 row_half_mirror row_mask:0xf bank_mask:0xf
	s_nop 1
	v_mov_b32_dpp v76, v74 row_half_mirror row_mask:0xf bank_mask:0xf
	s_waitcnt lgkmcnt(0)
	v_pk_add_f32 v[70:71], v[70:71], v[72:73]
	s_waitcnt lgkmcnt(0)
	v_pk_add_f32 v[74:75], v[74:75], v[76:77]
	v_pk_mul_f32 v[82:83], v[70:71], s[18:19] op_sel_hi:[1,0]
	s_nop 1
	v_mov_b32_dpp v77, v75 row_mirror row_mask:0xf bank_mask:0xf
	v_fma_f32 v0, -v83, v83, v82
	v_max_f32_e32 v0, 0, v0
	v_add_f32_e32 v0, 0x358637bd, v0
	v_mul_f32_e32 v70, 0x4f800000, v0
	v_cmp_gt_f32_e32 vcc, s16, v0
	s_nop 1
	v_mov_b32_dpp v76, v74 row_mirror row_mask:0xf bank_mask:0xf
	v_sub_f32_e32 v67, v67, v83
	v_cndmask_b32_e32 v0, v0, v70, vcc
	v_sqrt_f32_e32 v78, v0
	v_sub_f32_e32 v66, v66, v83
	s_waitcnt lgkmcnt(0)
	v_pk_add_f32 v[70:71], v[74:75], v[76:77]
	v_sub_f32_e32 v69, v69, v83
	v_add_u32_e32 v74, -1, v78
	v_fma_f32 v75, -v74, v78, v0
	v_cmp_ge_f32_e64 s[0:1], 0, v75
	v_add_u32_e32 v75, 1, v78
	v_fma_f32 v76, -v75, v78, v0
	v_cndmask_b32_e64 v74, v78, v74, s[0:1]
	v_cmp_lt_f32_e64 s[0:1], 0, v76
	v_sub_f32_e32 v68, v68, v83
	v_sub_f32_e32 v59, v59, v83
	v_cndmask_b32_e64 v74, v74, v75, s[0:1]
	v_mul_f32_e32 v75, 0x37800000, v74
	v_cndmask_b32_e32 v74, v74, v75, vcc
	v_cmp_class_f32_e32 vcc, v0, v217
	v_sub_f32_e32 v58, v58, v83
	v_sub_f32_e32 v61, v61, v83
	v_cndmask_b32_e32 v0, v74, v0, vcc
	v_div_scale_f32 v74, s[0:1], v0, v0, 1.0
	v_rcp_f32_e32 v75, v74
	s_lshl_b64 s[0:1], s[14:15], 11
	v_sub_f32_e32 v60, v60, v83
	ds_bpermute_b32 v73, v137, v71
	v_fma_f32 v76, -v74, v75, 1.0
	v_fmac_f32_e32 v75, v76, v75
	v_div_scale_f32 v76, vcc, 1.0, v0, 1.0
	v_mul_f32_e32 v77, v76, v75
	v_fma_f32 v78, -v74, v77, v76
	v_fmac_f32_e32 v77, v78, v75
	v_fma_f32 v74, -v74, v77, v76
	v_div_fmas_f32 v74, v74, v75, v77
	v_div_fixup_f32 v0, v74, v0, 1.0
	ds_read_b128 v[74:77], v127 offset:20480
	ds_read_b128 v[78:81], v127 offset:32768
	v_pk_mul_f32 v[66:67], v[66:67], v[0:1] op_sel_hi:[1,0]
	v_pk_mul_f32 v[68:69], v[68:69], v[0:1] op_sel_hi:[1,0]
	v_pk_mul_f32 v[58:59], v[58:59], v[0:1] op_sel_hi:[1,0]
	v_pk_mul_f32 v[60:61], v[60:61], v[0:1] op_sel_hi:[1,0]
	s_waitcnt lgkmcnt(0)
	v_pk_fma_f32 v[66:67], v[78:79], v[66:67], v[74:75]
	v_lshl_add_u64 v[78:79], v[106:107], 0, s[0:1]
	v_pk_fma_f32 v[68:69], v[80:81], v[68:69], v[76:77]
	v_cvt_pk_bf16_f32 v66, v66, v67
	ds_bpermute_b32 v72, v137, v70
	v_cvt_pk_bf16_f32 v67, v68, v69
	global_store_dwordx2 v[78:79], v[66:67], off
	ds_read_b128 v[66:69], v127 offset:21504
	ds_read_b128 v[74:77], v127 offset:33792
	v_sub_f32_e32 v55, v55, v83
	v_sub_f32_e32 v54, v54, v83
	v_sub_f32_e32 v57, v57, v83
	v_sub_f32_e32 v56, v56, v83
	s_waitcnt lgkmcnt(0)
	v_pk_fma_f32 v[58:59], v[74:75], v[58:59], v[66:67]
	v_pk_fma_f32 v[60:61], v[76:77], v[60:61], v[68:69]
	v_cvt_pk_bf16_f32 v58, v58, v59
	v_pk_mul_f32 v[54:55], v[54:55], v[0:1] op_sel_hi:[1,0]
	v_cvt_pk_bf16_f32 v59, v60, v61
	global_store_dwordx2 v[78:79], v[58:59], off offset:512
	ds_read_b128 v[58:61], v127 offset:22528
	ds_read_b128 v[66:69], v127 offset:34816
	v_pk_mul_f32 v[56:57], v[56:57], v[0:1] op_sel_hi:[1,0]
	v_pk_add_f32 v[70:71], v[70:71], v[72:73]
	ds_bpermute_b32 v73, v138, v71
	ds_bpermute_b32 v72, v138, v70
	s_waitcnt lgkmcnt(2)
	v_pk_fma_f32 v[54:55], v[54:55], v[66:67], v[58:59]
	v_pk_fma_f32 v[56:57], v[56:57], v[68:69], v[60:61]
	v_cvt_pk_bf16_f32 v54, v54, v55
	v_sub_f32_e32 v63, v63, v83
	v_cvt_pk_bf16_f32 v55, v56, v57
	global_store_dwordx2 v[78:79], v[54:55], off offset:1024
	ds_read_b128 v[54:57], v127 offset:23552
	ds_read_b128 v[58:61], v127 offset:35840
	v_sub_f32_e32 v62, v62, v83
	v_sub_f32_e32 v65, v65, v83
	v_sub_f32_e32 v64, v64, v83
	v_pk_mul_f32 v[62:63], v[62:63], v[0:1] op_sel_hi:[1,0]
	v_pk_mul_f32 v[64:65], v[64:65], v[0:1] op_sel_hi:[1,0]
	s_waitcnt lgkmcnt(0)
	v_pk_fma_f32 v[54:55], v[62:63], v[58:59], v[54:55]
	s_and_b64 vcc, exec, s[4:5]
	v_pk_fma_f32 v[56:57], v[64:65], v[60:61], v[56:57]
	v_cvt_pk_bf16_f32 v54, v54, v55
	s_nop 0
	v_cvt_pk_bf16_f32 v55, v56, v57
	global_store_dwordx2 v[78:79], v[54:55], off offset:1536
	s_cbranch_vccnz .LBB0_996
; #define LAS __attribute__((address_space(3)))
; __device__ __forceinline__ unsigned cvt_pk_bf16(float lo, float hi) { unsigned r; asm volatile("v_cvt_pk_bf16_f32 %0, %1, %2" : "=v"(r) : "v"(lo), "v"(hi)); return r; }
; __device__ __forceinline__ void row_pass(const Params& P, int l, int mode, LAS float* pl) {
;     ...
;             for (int r = 0; r < 2; ++r) if (ok[r]) { const float mean = s[r] * (1.f / DM); const float var = fmaxf(q[r] * (1.f / DM) - mean * mean, 0.f); const float rstd = 1.f / sqrtf(var + LN_EPS);
;                 const LAS float* mm = pl + 5120 + mv[r] * DM;
; #pragma unroll
;                 for (int j = 0; j < 4; ++j) { const f32x4 sh = *(const LAS f32x4*)(mm + 4 * lane + 256 * j), sc1 = *(const LAS f32x4*)(mm + 3072 + 4 * lane + 256 * j);
;                     const f32x4 hv = (v[r][j] - mean) * rstd * sc1 + sh; u32x2 o; o.x = cvt_pk_bf16(hv[0], hv[1]); o.y = cvt_pk_bf16(hv[2], hv[3]);
;                     *(u32x2*)(H + (size_t)row[r] * DM + 4 * lane + 256 * j) = o; } }
	v_pk_add_f32 v[54:55], v[70:71], v[72:73]
	s_nop 0
	v_pk_mul_f32 v[62:63], v[54:55], s[18:19] op_sel_hi:[1,0]
	s_nop 0
	v_fma_f32 v0, -v63, v63, v62
	v_max_f32_e32 v0, 0, v0
	v_add_f32_e32 v0, 0x358637bd, v0
	v_mul_f32_e32 v54, 0x4f800000, v0
	v_cmp_gt_f32_e32 vcc, s16, v0
	v_sub_f32_e32 v51, v51, v63
	v_sub_f32_e32 v50, v50, v63
	v_cndmask_b32_e32 v0, v0, v54, vcc
	v_sqrt_f32_e32 v54, v0
	v_sub_f32_e32 v53, v53, v63
	v_sub_f32_e32 v52, v52, v63
	v_sub_f32_e32 v47, v47, v63
	v_add_u32_e32 v55, -1, v54
	v_fma_f32 v57, -v55, v54, v0
	v_add_u32_e32 v56, 1, v54
	v_cmp_ge_f32_e64 s[0:1], 0, v57
	v_sub_f32_e32 v46, v46, v63
	v_sub_f32_e32 v49, v49, v63
	v_cndmask_b32_e64 v55, v54, v55, s[0:1]
	v_fma_f32 v54, -v56, v54, v0
	v_cmp_lt_f32_e64 s[0:1], 0, v54
	v_sub_f32_e32 v48, v48, v63
	v_sub_f32_e32 v43, v43, v63
	v_cndmask_b32_e64 v54, v55, v56, s[0:1]
	v_mul_f32_e32 v55, 0x37800000, v54
	v_cndmask_b32_e32 v54, v54, v55, vcc
	v_cmp_class_f32_e32 vcc, v0, v217
	v_sub_f32_e32 v42, v42, v63
	v_sub_f32_e32 v45, v45, v63
	v_cndmask_b32_e32 v0, v54, v0, vcc
	v_div_scale_f32 v54, s[0:1], v0, v0, 1.0
	v_rcp_f32_e32 v55, v54
	s_lshl_b64 s[0:1], s[10:11], 11
	v_sub_f32_e32 v44, v44, v63
	v_sub_f32_e32 v39, v39, v63
	v_fma_f32 v56, -v54, v55, 1.0
	v_fmac_f32_e32 v55, v56, v55
	v_div_scale_f32 v56, vcc, 1.0, v0, 1.0
	v_mul_f32_e32 v57, v56, v55
	v_fma_f32 v58, -v54, v57, v56
	v_fmac_f32_e32 v57, v58, v55
	v_fma_f32 v54, -v54, v57, v56
	v_div_fmas_f32 v54, v54, v55, v57
	v_div_fixup_f32 v0, v54, v0, 1.0
	ds_read_b128 v[54:57], v126 offset:20480
	ds_read_b128 v[58:61], v126 offset:32768
	v_pk_mul_f32 v[50:51], v[50:51], v[0:1] op_sel_hi:[1,0]
	v_pk_mul_f32 v[52:53], v[52:53], v[0:1] op_sel_hi:[1,0]
	v_pk_mul_f32 v[46:47], v[46:47], v[0:1] op_sel_hi:[1,0]
	v_pk_mul_f32 v[48:49], v[48:49], v[0:1] op_sel_hi:[1,0]
	s_waitcnt lgkmcnt(0)
	v_pk_fma_f32 v[50:51], v[50:51], v[58:59], v[54:55]
	v_lshl_add_u64 v[58:59], v[106:107], 0, s[0:1]
	v_pk_fma_f32 v[52:53], v[52:53], v[60:61], v[56:57]
	v_cvt_pk_bf16_f32 v50, v50, v51
	v_pk_mul_f32 v[42:43], v[42:43], v[0:1] op_sel_hi:[1,0]
	v_cvt_pk_bf16_f32 v51, v52, v53
	global_store_dwordx2 v[58:59], v[50:51], off
	ds_read_b128 v[50:53], v126 offset:21504
	ds_read_b128 v[54:57], v126 offset:33792
	v_pk_mul_f32 v[44:45], v[44:45], v[0:1] op_sel_hi:[1,0]
	v_sub_f32_e32 v38, v38, v63
	v_sub_f32_e32 v41, v41, v63
	v_sub_f32_e32 v40, v40, v63
	s_waitcnt lgkmcnt(0)
	v_pk_fma_f32 v[46:47], v[46:47], v[54:55], v[50:51]
	v_pk_fma_f32 v[48:49], v[48:49], v[56:57], v[52:53]
	v_cvt_pk_bf16_f32 v46, v46, v47
	v_pk_mul_f32 v[38:39], v[38:39], v[0:1] op_sel_hi:[1,0]
	v_cvt_pk_bf16_f32 v47, v48, v49
	global_store_dwordx2 v[58:59], v[46:47], off offset:512
	ds_read_b128 v[46:49], v126 offset:22528
	ds_read_b128 v[50:53], v126 offset:34816
	v_pk_mul_f32 v[40:41], v[40:41], v[0:1] op_sel_hi:[1,0]
	s_waitcnt lgkmcnt(0)
	v_pk_fma_f32 v[42:43], v[42:43], v[50:51], v[46:47]
	v_pk_fma_f32 v[44:45], v[44:45], v[52:53], v[48:49]
	v_cvt_pk_bf16_f32 v42, v42, v43
	s_nop 0
	v_cvt_pk_bf16_f32 v43, v44, v45
	global_store_dwordx2 v[58:59], v[42:43], off offset:1024
	ds_read_b128 v[42:45], v126 offset:23552
	ds_read_b128 v[46:49], v126 offset:35840
	s_waitcnt lgkmcnt(0)
	v_pk_fma_f32 v[38:39], v[38:39], v[46:47], v[42:43]
	v_pk_fma_f32 v[40:41], v[40:41], v[48:49], v[44:45]
	v_cvt_pk_bf16_f32 v38, v38, v39
	s_nop 0
	v_cvt_pk_bf16_f32 v39, v40, v41
	global_store_dwordx2 v[58:59], v[38:39], off offset:1536
	s_branch .LBB0_996

; #define LAS __attribute__((address_space(3)))
; __device__ __forceinline__ void wave_sum2(float& a, float& b) {
; #pragma unroll
;     for (int o = 1; o < 64; o <<= 1) { const float ta = __shfl_xor(a, o), tb = __shfl_xor(b, o); a += ta; b += tb; }
; }
; __device__ __forceinline__ void row_pass(const Params& P, int l, int mode, LAS float* pl) {
;     ...
;         if (mode != 0) {
;             float s[2], q[2];
; #pragma unroll
;             for (int r = 0; r < 2; ++r) { const LAS float* gm = pl + mv[r] * DM; s[r] = 0.f; q[r] = 0.f;
; #pragma unroll
;                 for (int j = 0; j < 4; ++j) { const f32x4 g = *(const LAS f32x4*)(gm + 4 * lane + 256 * j); v[r][j] = v[r][j] * ALPHA + g * yv[r][j];
;                     s[r] += (v[r][j][0] + v[r][j][1]) + (v[r][j][2] + v[r][j][3]); const f32x4 sq = v[r][j] * v[r][j]; q[r] += (sq[0] + sq[1]) + (sq[2] + sq[3]); } }
;             wave_sum2(s[0], s[1]); wave_sum2(q[0], q[1]);
.LBB0_1305:
	s_mul_i32 s18, s26, 0x2100
	s_mul_i32 s19, s21, 0x2100
	s_add_i32 s18, s18, s22
	s_add_i32 s20, s19, s20
	s_and_b64 s[22:23], s[38:39], exec
	s_cselect_b32 s22, s2, s20
	s_ashr_i32 s23, s22, 31
	s_lshl_b64 s[22:23], s[22:23], 12
	s_add_u32 s22, s14, s22
	s_addc_u32 s23, s15, s23
	s_lshl_b32 s2, s21, 12
	s_and_b64 s[0:1], s[0:1], exec
	s_cselect_b32 s0, s2, 0x2000
	v_add_u32_e32 v98, s0, v15
	ds_read_b128 v[100:103], v98
	ds_read_b128 v[104:107], v98 offset:1024
	s_mov_b32 s30, 0x3fd744fd
	s_lshl_b32 s2, s26, 12
	s_and_b64 s[0:1], exec, s[10:11]
	s_waitcnt lgkmcnt(1)
	v_pk_mul_f32 v[72:73], v[102:103], v[72:73]
	v_pk_mul_f32 v[70:71], v[100:101], v[70:71]
	v_pk_fma_f32 v[68:69], v[68:69], s[30:31], v[72:73] op_sel_hi:[1,0,1]
	ds_read_b128 v[100:103], v98 offset:2048
	v_pk_fma_f32 v[66:67], v[66:67], s[30:31], v[70:71] op_sel_hi:[1,0,1]
	v_pk_mul_f32 v[70:71], v[68:69], v[68:69]
	s_waitcnt lgkmcnt(1)
	v_pk_mul_f32 v[72:73], v[106:107], v[76:77]
	v_add_f32_e32 v0, v70, v71
	v_pk_mul_f32 v[70:71], v[104:105], v[74:75]
	v_pk_fma_f32 v[74:75], v[64:65], s[30:31], v[72:73] op_sel_hi:[1,0,1]
	v_pk_fma_f32 v[70:71], v[62:63], s[30:31], v[70:71] op_sel_hi:[1,0,1]
	ds_read_b128 v[62:65], v98 offset:3072
	v_pk_mul_f32 v[106:107], v[70:71], v[70:71]
	v_pk_mul_f32 v[112:113], v[66:67], v[66:67]
	v_pk_mul_f32 v[104:105], v[74:75], v[74:75]
	s_waitcnt lgkmcnt(1)
	v_pk_mul_f32 v[76:77], v[102:103], v[84:85]
	v_pk_mul_f32 v[72:73], v[100:101], v[82:83]
	v_mov_b32_e32 v100, v106
	v_mov_b32_e32 v101, v70
	v_mov_b32_e32 v102, v107
	v_mov_b32_e32 v103, v71
	v_add_f32_e32 v109, v66, v67
	v_add_f32_e32 v111, v68, v69
	v_mov_b32_e32 v108, v112
	v_mov_b32_e32 v110, v113
	v_pk_add_f32 v[100:101], v[100:101], v[102:103]
	v_mov_b32_e32 v102, v104
	v_mov_b32_e32 v103, v74
	v_mov_b32_e32 v104, v105
	v_mov_b32_e32 v105, v75
	v_pk_fma_f32 v[72:73], v[58:59], s[30:31], v[72:73] op_sel_hi:[1,0,1]
	v_pk_add_f32 v[84:85], v[108:109], v[110:111]
	v_pk_add_f32 v[102:103], v[102:103], v[104:105]
	v_pk_fma_f32 v[76:77], v[60:61], s[30:31], v[76:77] op_sel_hi:[1,0,1]
	v_pk_mul_f32 v[60:61], v[72:73], v[72:73]
	v_pk_add_f32 v[84:85], v[84:85], v[0:1]
	v_pk_add_f32 v[100:101], v[100:101], v[102:103]
	v_pk_mul_f32 v[58:59], v[76:77], v[76:77]
	s_waitcnt lgkmcnt(0)
	v_pk_mul_f32 v[62:63], v[62:63], v[78:79]
	v_pk_add_f32 v[84:85], v[84:85], v[100:101]
	v_mov_b32_e32 v100, v60
	v_mov_b32_e32 v101, v72
	v_mov_b32_e32 v60, v61
	v_mov_b32_e32 v61, v73
	v_pk_mul_f32 v[64:65], v[64:65], v[80:81]
	v_pk_fma_f32 v[62:63], v[54:55], s[30:31], v[62:63] op_sel_hi:[1,0,1]
	v_pk_add_f32 v[60:61], v[100:101], v[60:61]
	v_mov_b32_e32 v100, v58
	v_mov_b32_e32 v101, v76
	v_mov_b32_e32 v58, v59
	v_mov_b32_e32 v59, v77
	v_pk_fma_f32 v[64:65], v[56:57], s[30:31], v[64:65] op_sel_hi:[1,0,1]
	v_pk_mul_f32 v[82:83], v[62:63], v[62:63]
	v_pk_add_f32 v[58:59], v[100:101], v[58:59]
	v_pk_mul_f32 v[78:79], v[64:65], v[64:65]
	v_pk_add_f32 v[58:59], v[60:61], v[58:59]
	v_mov_b32_e32 v60, v82
	v_mov_b32_e32 v61, v62
	v_mov_b32_e32 v82, v83
	v_mov_b32_e32 v83, v63
	v_pk_add_f32 v[60:61], v[60:61], v[82:83]
	v_mov_b32_e32 v82, v78
	v_mov_b32_e32 v83, v64
	v_mov_b32_e32 v78, v79
	v_mov_b32_e32 v79, v65
	s_cselect_b32 s0, s2, 0x2000
	v_pk_add_f32 v[78:79], v[82:83], v[78:79]
	v_add_u32_e32 v80, s0, v15
	v_pk_add_f32 v[58:59], v[84:85], v[58:59]
	v_pk_add_f32 v[60:61], v[60:61], v[78:79]
	ds_read_b128 v[54:57], v80
	v_pk_add_f32 v[78:79], v[58:59], v[60:61]
	s_nop 1
	v_mov_b32_dpp v83, v79 quad_perm:[1,0,3,2] row_mask:0xf bank_mask:0xf
	s_nop 1
	v_mov_b32_dpp v82, v78 quad_perm:[1,0,3,2] row_mask:0xf bank_mask:0xf
	ds_read_b128 v[58:61], v80 offset:1024
	s_waitcnt lgkmcnt(0)
	v_pk_mul_f32 v[56:57], v[56:57], v[88:89]
	v_pk_mul_f32 v[54:55], v[54:55], v[86:87]
	v_pk_fma_f32 v[52:53], v[52:53], s[30:31], v[56:57] op_sel_hi:[1,0,1]
	s_waitcnt lgkmcnt(0)
	v_pk_add_f32 v[56:57], v[78:79], v[82:83]
	s_nop 1
	v_mov_b32_dpp v79, v57 quad_perm:[2,3,0,1] row_mask:0xf bank_mask:0xf
	s_nop 1
	v_mov_b32_dpp v78, v56 quad_perm:[2,3,0,1] row_mask:0xf bank_mask:0xf
	v_pk_fma_f32 v[50:51], v[50:51], s[30:31], v[54:55] op_sel_hi:[1,0,1]
	s_mov_b32 s10, 0x3a800000
	s_waitcnt lgkmcnt(0)
	v_pk_mul_f32 v[60:61], v[60:61], v[92:93]
	v_pk_mul_f32 v[58:59], v[58:59], v[90:91]
	s_waitcnt lgkmcnt(0)
	v_pk_add_f32 v[54:55], v[56:57], v[78:79]
	s_nop 1
	v_mov_b32_dpp v57, v55 row_half_mirror row_mask:0xf bank_mask:0xf
	s_nop 1
	v_mov_b32_dpp v56, v54 row_half_mirror row_mask:0xf bank_mask:0xf
	v_pk_mul_f32 v[78:79], v[52:53], v[52:53]
	v_pk_fma_f32 v[46:47], v[46:47], s[30:31], v[58:59] op_sel_hi:[1,0,1]
	v_add_f32_e32 v106, v78, v79
	v_pk_fma_f32 v[48:49], v[48:49], s[30:31], v[60:61] op_sel_hi:[1,0,1]
	s_waitcnt lgkmcnt(0)
	v_pk_add_f32 v[78:79], v[54:55], v[56:57]
	s_nop 1
	v_mov_b32_dpp v83, v79 row_mirror row_mask:0xf bank_mask:0xf
	s_nop 1
	v_mov_b32_dpp v82, v78 row_mirror row_mask:0xf bank_mask:0xf
	ds_read_b128 v[54:57], v80 offset:2048
	ds_read_b128 v[58:61], v80 offset:3072
	v_pk_mul_f32 v[104:105], v[50:51], v[50:51]
	v_add_f32_e32 v101, v50, v51
	s_waitcnt lgkmcnt(0)
	v_pk_add_f32 v[78:79], v[78:79], v[82:83]
	ds_bpermute_b32 v83, v195, v79
	ds_bpermute_b32 v82, v195, v78
	s_waitcnt lgkmcnt(0)
	v_pk_mul_f32 v[58:59], v[58:59], v[138:139]
	v_add_f32_e32 v103, v52, v53
	v_pk_mul_f32 v[110:111], v[46:47], v[46:47]
	v_pk_fma_f32 v[38:39], v[38:39], s[30:31], v[58:59] op_sel_hi:[1,0,1]
	s_waitcnt lgkmcnt(0)
	v_pk_add_f32 v[78:79], v[78:79], v[82:83]
	ds_bpermute_b32 v83, v196, v79
	ds_bpermute_b32 v82, v196, v78
	v_mov_b32_e32 v100, v104
	v_mov_b32_e32 v102, v105
	v_pk_mul_f32 v[108:109], v[48:49], v[48:49]
	v_pk_add_f32 v[100:101], v[100:101], v[102:103]
	s_waitcnt lgkmcnt(0)
; #define LAS __attribute__((address_space(3)))
; __device__ __forceinline__ void row_pass(const Params& P, int l, int mode, LAS float* pl) {
;     ...
;             wave_sum2(s[0], s[1]); wave_sum2(q[0], q[1]);
; #pragma unroll
;             for (int r = 0; r < 2; ++r) { const float mean = s[r] * (1.f / DM); const float var = fmaxf(q[r] * (1.f / DM) - mean * mean, 0.f); const float rstd = 1.f / sqrtf(var + LN_EPS);
; #pragma unroll
;                 for (int j = 0; j < 4; ++j) { const f32x4 g = *(const LAS f32x4*)(pl + 3072 + 4 * lane + 256 * j), bb = *(const LAS f32x4*)(pl + 4096 + 4 * lane + 256 * j); v[r][j] = (v[r][j] - mean) * rstd * g + bb; } }
	v_pk_add_f32 v[78:79], v[78:79], v[82:83]
	v_mov_b32_e32 v107, v1
	v_pk_mul_f32 v[78:79], v[78:79], s[10:11] op_sel_hi:[1,0]
	v_mov_b32_e32 v102, v110
	v_fma_f32 v0, -v79, v79, v78
	v_max_f32_e32 v0, 0, v0
	v_add_f32_e32 v0, 0x358637bd, v0
	v_mul_f32_e32 v78, 0x4f800000, v0
	v_cmp_gt_f32_e32 vcc, s69, v0
	v_mov_b32_e32 v103, v46
	v_mov_b32_e32 v104, v111
	v_cndmask_b32_e32 v0, v0, v78, vcc
	v_sqrt_f32_e32 v78, v0
	v_mov_b32_e32 v105, v47
	v_pk_mul_f32 v[54:55], v[54:55], v[94:95]
	v_pk_add_f32 v[100:101], v[100:101], v[106:107]
	v_add_u32_e32 v58, -1, v78
	v_fma_f32 v59, -v58, v78, v0
	v_cmp_ge_f32_e64 s[0:1], 0, v59
	v_add_u32_e32 v59, 1, v78
	v_pk_add_f32 v[102:103], v[102:103], v[104:105]
	v_mov_b32_e32 v104, v108
	v_mov_b32_e32 v105, v48
	v_mov_b32_e32 v106, v109
	v_mov_b32_e32 v107, v49
	v_pk_mul_f32 v[56:57], v[56:57], v[96:97]
	v_pk_fma_f32 v[42:43], v[42:43], s[30:31], v[54:55] op_sel_hi:[1,0,1]
	v_cndmask_b32_e64 v58, v78, v58, s[0:1]
	v_fma_f32 v78, -v59, v78, v0
	v_pk_add_f32 v[104:105], v[104:105], v[106:107]
	v_pk_fma_f32 v[44:45], v[44:45], s[30:31], v[56:57] op_sel_hi:[1,0,1]
	v_pk_mul_f32 v[56:57], v[42:43], v[42:43]
	v_cmp_lt_f32_e64 s[0:1], 0, v78
	v_pk_add_f32 v[102:103], v[102:103], v[104:105]
	v_pk_mul_f32 v[54:55], v[44:45], v[44:45]
	v_cndmask_b32_e64 v58, v58, v59, s[0:1]
	v_pk_add_f32 v[100:101], v[100:101], v[102:103]
	v_mov_b32_e32 v102, v56
	v_mov_b32_e32 v103, v42
	v_mov_b32_e32 v56, v57
	v_mov_b32_e32 v57, v43
	v_pk_mul_f32 v[60:61], v[60:61], v[140:141]
	v_mul_f32_e32 v59, 0x37800000, v58
	v_pk_add_f32 v[56:57], v[102:103], v[56:57]
	v_mov_b32_e32 v102, v54
	v_mov_b32_e32 v103, v44
	v_mov_b32_e32 v54, v55
	v_mov_b32_e32 v55, v45
	v_cndmask_b32_e32 v58, v58, v59, vcc
	v_cmp_class_f32_e32 vcc, v0, v217
	v_pk_fma_f32 v[40:41], v[40:41], s[30:31], v[60:61] op_sel_hi:[1,0,1]
	v_pk_mul_f32 v[60:61], v[38:39], v[38:39]
	v_pk_add_f32 v[54:55], v[102:103], v[54:55]
	v_cndmask_b32_e32 v0, v58, v0, vcc
	v_pk_mul_f32 v[58:59], v[40:41], v[40:41]
	v_pk_add_f32 v[54:55], v[56:57], v[54:55]
	v_mov_b32_e32 v56, v60
	v_mov_b32_e32 v57, v38
	v_mov_b32_e32 v60, v61
	v_mov_b32_e32 v61, v39
	v_pk_add_f32 v[56:57], v[56:57], v[60:61]
	v_mov_b32_e32 v60, v58
	v_mov_b32_e32 v61, v40
	v_mov_b32_e32 v58, v59
	v_mov_b32_e32 v59, v41
	v_pk_add_f32 v[58:59], v[60:61], v[58:59]
	v_pk_add_f32 v[54:55], v[100:101], v[54:55]
	v_pk_add_f32 v[56:57], v[56:57], v[58:59]
	v_div_scale_f32 v78, s[0:1], v0, v0, 1.0
	v_pk_add_f32 v[54:55], v[54:55], v[56:57]
	s_nop 1
	v_mov_b32_dpp v57, v55 quad_perm:[1,0,3,2] row_mask:0xf bank_mask:0xf
	s_nop 1
	v_mov_b32_dpp v56, v54 quad_perm:[1,0,3,2] row_mask:0xf bank_mask:0xf
	v_rcp_f32_e32 v81, v78
	v_sub_f32_e32 v59, v75, v79
	v_sub_f32_e32 v58, v74, v79
	v_sub_f32_e32 v61, v71, v79
	s_waitcnt lgkmcnt(0)
	v_pk_add_f32 v[54:55], v[54:55], v[56:57]
	s_nop 1
	v_mov_b32_dpp v57, v55 quad_perm:[2,3,0,1] row_mask:0xf bank_mask:0xf
	s_nop 1
	v_mov_b32_dpp v56, v54 quad_perm:[2,3,0,1] row_mask:0xf bank_mask:0xf
	v_fma_f32 v82, -v78, v81, 1.0
	v_fmac_f32_e32 v81, v82, v81
	v_div_scale_f32 v82, vcc, 1.0, v0, 1.0
	s_waitcnt lgkmcnt(0)
	v_pk_add_f32 v[54:55], v[54:55], v[56:57]
	s_nop 1
	v_mov_b32_dpp v57, v55 row_half_mirror row_mask:0xf bank_mask:0xf
	s_nop 1
	v_mov_b32_dpp v56, v54 row_half_mirror row_mask:0xf bank_mask:0xf
	v_mul_f32_e32 v83, v82, v81
	v_fma_f32 v84, -v78, v83, v82
	v_fmac_f32_e32 v83, v84, v81
	v_fma_f32 v78, -v78, v83, v82
	s_waitcnt lgkmcnt(0)
	v_pk_add_f32 v[54:55], v[54:55], v[56:57]
	s_nop 1
	v_mov_b32_dpp v57, v55 row_mirror row_mask:0xf bank_mask:0xf
	s_nop 1
	v_mov_b32_dpp v56, v54 row_mirror row_mask:0xf bank_mask:0xf
	v_div_fmas_f32 v78, v78, v81, v83
	ds_read_b128 v[82:85], v15 offset:12288
	ds_read_b128 v[86:89], v15 offset:13312
	ds_read_b128 v[90:93], v15 offset:16384
	ds_read_b128 v[94:97], v15 offset:17408
	v_div_fixup_f32 v0, v78, v0, 1.0
	v_sub_f32_e32 v60, v70, v79
	s_waitcnt lgkmcnt(0)
	v_pk_add_f32 v[54:55], v[54:55], v[56:57]
	ds_bpermute_b32 v57, v195, v55
	ds_bpermute_b32 v56, v195, v54
	v_pk_mul_f32 v[70:71], v[60:61], v[0:1] op_sel_hi:[1,0]
	v_pk_mul_f32 v[58:59], v[58:59], v[0:1] op_sel_hi:[1,0]
	v_sub_f32_e32 v73, v73, v79
	s_waitcnt lgkmcnt(0)
	v_pk_fma_f32 v[60:61], v[88:89], v[58:59], v[96:97]
	s_waitcnt lgkmcnt(0)
	v_pk_add_f32 v[112:113], v[54:55], v[56:57]
	v_pk_fma_f32 v[58:59], v[86:87], v[70:71], v[94:95]
	v_sub_f32_e32 v71, v77, v79
	v_sub_f32_e32 v70, v76, v79
	v_sub_f32_e32 v72, v72, v79
	ds_bpermute_b32 v115, v196, v113
	ds_bpermute_b32 v114, v196, v112
	v_pk_mul_f32 v[108:109], v[72:73], v[0:1] op_sel_hi:[1,0]
	v_pk_mul_f32 v[110:111], v[70:71], v[0:1] op_sel_hi:[1,0]
	ds_read_b128 v[70:73], v15 offset:14336
	ds_read_b128 v[74:77], v15 offset:15360
	ds_read_b128 v[100:103], v15 offset:18432
	ds_read_b128 v[104:107], v15 offset:19456
	v_sub_f32_e32 v69, v69, v79
	v_sub_f32_e32 v68, v68, v79
	v_sub_f32_e32 v67, v67, v79
	s_waitcnt lgkmcnt(1)
; #define LAS __attribute__((address_space(3)))
; __device__ __forceinline__ void row_pass(const Params& P, int l, int mode, LAS float* pl) {
;     ...
;             for (int r = 0; r < 2; ++r) { const float mean = s[r] * (1.f / DM); const float var = fmaxf(q[r] * (1.f / DM) - mean * mean, 0.f); const float rstd = 1.f / sqrtf(var + LN_EPS);
; #pragma unroll
;                 for (int j = 0; j < 4; ++j) { const f32x4 g = *(const LAS f32x4*)(pl + 3072 + 4 * lane + 256 * j), bb = *(const LAS f32x4*)(pl + 4096 + 4 * lane + 256 * j); v[r][j] = (v[r][j] - mean) * rstd * g + bb; } }
;         }
;         if (mode != 0) {
; #pragma unroll
;         for (int r = 0; r < 2; ++r) if (ok[r]) {
; #pragma unroll
;             for (int j = 0; j < 4; ++j) __builtin_nontemporal_store(v[r][j], (f32x4*)(dst[r] + 4 * lane + 256 * j)); } }
;         if (make_h) {
;             float s[2], q[2];
; #pragma unroll
;             for (int r = 0; r < 2; ++r) { s[r] = 0.f; q[r] = 0.f;
; #pragma unroll
;                 for (int j = 0; j < 4; ++j) { s[r] += (v[r][j][0] + v[r][j][1]) + (v[r][j][2] + v[r][j][3]); const f32x4 sq = v[r][j] * v[r][j]; q[r] += (sq[0] + sq[1]) + (sq[2] + sq[3]); } }
	v_pk_fma_f32 v[54:55], v[70:71], v[108:109], v[100:101]
	v_pk_add_f32 v[108:109], v[112:113], v[114:115]
	v_sub_f32_e32 v66, v66, v79
	v_pk_mul_f32 v[108:109], v[108:109], s[10:11] op_sel_hi:[1,0]
	v_sub_f32_e32 v65, v65, v79
	v_fma_f32 v78, -v109, v109, v108
	v_max_f32_e32 v78, 0, v78
	v_add_f32_e32 v78, 0x358637bd, v78
	v_mul_f32_e32 v81, 0x4f800000, v78
	v_cmp_gt_f32_e32 vcc, s69, v78
	v_sub_f32_e32 v64, v64, v79
	v_sub_f32_e32 v63, v63, v79
	v_cndmask_b32_e32 v78, v78, v81, vcc
	v_sqrt_f32_e32 v81, v78
	v_sub_f32_e32 v62, v62, v79
	v_pk_mul_f32 v[66:67], v[66:67], v[0:1] op_sel_hi:[1,0]
	v_pk_mul_f32 v[68:69], v[68:69], v[0:1] op_sel_hi:[1,0]
	v_add_u32_e32 v79, -1, v81
	v_fma_f32 v99, -v79, v81, v78
	v_cmp_ge_f32_e64 s[0:1], 0, v99
	v_add_u32_e32 v99, 1, v81
	v_pk_mul_f32 v[62:63], v[62:63], v[0:1] op_sel_hi:[1,0]
	v_cndmask_b32_e64 v79, v81, v79, s[0:1]
	v_fma_f32 v81, -v99, v81, v78
	v_cmp_lt_f32_e64 s[0:1], 0, v81
	v_pk_mul_f32 v[64:65], v[64:65], v[0:1] op_sel_hi:[1,0]
	v_sub_f32_e32 v43, v43, v109
	v_cndmask_b32_e64 v79, v79, v99, s[0:1]
	v_mul_f32_e32 v81, 0x37800000, v79
	v_cndmask_b32_e32 v79, v79, v81, vcc
	v_cmp_class_f32_e32 vcc, v78, v217
	v_sub_f32_e32 v42, v42, v109
	v_sub_f32_e32 v53, v53, v109
	v_cndmask_b32_e32 v78, v79, v78, vcc
	v_div_scale_f32 v79, s[0:1], v78, v78, 1.0
	v_rcp_f32_e32 v81, v79
	v_sub_f32_e32 v52, v52, v109
	v_sub_f32_e32 v51, v51, v109
	v_sub_f32_e32 v50, v50, v109
	v_fma_f32 v0, -v79, v81, 1.0
	v_fmac_f32_e32 v81, v0, v81
	v_div_scale_f32 v0, vcc, 1.0, v78, 1.0
	v_mul_f32_e32 v99, v0, v81
	v_fma_f32 v108, -v79, v99, v0
	v_fmac_f32_e32 v99, v108, v81
	v_fma_f32 v0, -v79, v99, v0
	v_div_fmas_f32 v0, v0, v81, v99
	v_div_fixup_f32 v0, v0, v78, 1.0
	v_sub_f32_e32 v49, v49, v109
	v_sub_f32_e32 v48, v48, v109
	v_sub_f32_e32 v47, v47, v109
	v_sub_f32_e32 v46, v46, v109
	v_sub_f32_e32 v45, v45, v109
	v_sub_f32_e32 v44, v44, v109
	v_pk_mul_f32 v[42:43], v[42:43], v[0:1] op_sel_hi:[1,0]
	v_sub_f32_e32 v41, v41, v109
	v_sub_f32_e32 v40, v40, v109
	v_sub_f32_e32 v39, v39, v109
	v_sub_f32_e32 v38, v38, v109
	v_pk_mul_f32 v[50:51], v[50:51], v[0:1] op_sel_hi:[1,0]
	v_pk_mul_f32 v[52:53], v[52:53], v[0:1] op_sel_hi:[1,0]
	v_pk_mul_f32 v[46:47], v[46:47], v[0:1] op_sel_hi:[1,0]
	v_pk_mul_f32 v[48:49], v[48:49], v[0:1] op_sel_hi:[1,0]
	v_pk_mul_f32 v[44:45], v[44:45], v[0:1] op_sel_hi:[1,0]
	v_pk_fma_f32 v[42:43], v[70:71], v[42:43], v[100:101]
	v_pk_mul_f32 v[38:39], v[38:39], v[0:1] op_sel_hi:[1,0]
	v_pk_mul_f32 v[40:41], v[40:41], v[0:1] op_sel_hi:[1,0]
	v_cndmask_b32_e64 v70, 0, 1, s[16:17]
	v_pk_fma_f32 v[68:69], v[84:85], v[68:69], v[92:93]
	v_pk_fma_f32 v[66:67], v[82:83], v[66:67], v[90:91]
	v_pk_fma_f32 v[56:57], v[72:73], v[110:111], v[102:103]
	s_mov_b32 s2, 0x3a800000
	s_waitcnt lgkmcnt(0)
	v_pk_fma_f32 v[64:65], v[76:77], v[64:65], v[106:107]
	v_pk_fma_f32 v[62:63], v[74:75], v[62:63], v[104:105]
	v_pk_fma_f32 v[52:53], v[84:85], v[52:53], v[92:93]
	v_pk_fma_f32 v[50:51], v[82:83], v[50:51], v[90:91]
	v_pk_fma_f32 v[48:49], v[88:89], v[48:49], v[96:97]
	v_pk_fma_f32 v[46:47], v[86:87], v[46:47], v[94:95]
	v_pk_fma_f32 v[44:45], v[72:73], v[44:45], v[102:103]
	v_pk_fma_f32 v[40:41], v[76:77], v[40:41], v[106:107]
	v_pk_fma_f32 v[38:39], v[74:75], v[38:39], v[104:105]
	v_lshlrev_b32_e32 v0, 2, v14
	v_cmp_ne_u32_e64 s[10:11], 1, v70
	s_andn2_b64 vcc, exec, s[16:17]
	global_store_dwordx4 v0, v[66:69], s[22:23] nt
	global_store_dwordx4 v0, v[58:61], s[22:23] offset:1024 nt
	global_store_dwordx4 v0, v[54:57], s[22:23] offset:2048 nt
	global_store_dwordx4 v0, v[62:65], s[22:23] offset:3072 nt
	s_cbranch_vccnz .LBB0_1307
	s_and_b64 s[0:1], s[38:39], exec
	s_cselect_b32 s0, s25, s18
	s_ashr_i32 s1, s0, 31
	s_lshl_b64 s[0:1], s[0:1], 12
	s_add_u32 s0, s14, s0
	s_addc_u32 s1, s15, s1
	global_store_dwordx4 v0, v[50:53], s[0:1] nt
	global_store_dwordx4 v0, v[46:49], s[0:1] offset:1024 nt
	global_store_dwordx4 v0, v[42:45], s[0:1] offset:2048 nt
	global_store_dwordx4 v0, v[38:41], s[0:1] offset:3072 nt
.LBB0_1307:
	s_and_b64 vcc, exec, s[8:9]
	s_cbranch_vccnz .LBB0_1310
	v_pk_mul_f32 v[100:101], v[50:51], v[50:51]
	v_pk_mul_f32 v[96:97], v[52:53], v[52:53]
	v_pk_mul_f32 v[104:105], v[46:47], v[46:47]
	v_mov_b32_e32 v112, v100
	v_mov_b32_e32 v113, v46
	v_mov_b32_e32 v100, v101
	v_mov_b32_e32 v101, v47
	v_add_f32_e32 v93, v50, v51
	v_add_f32_e32 v95, v52, v53
	v_pk_mul_f32 v[102:103], v[48:49], v[48:49]
	v_pk_add_f32 v[100:101], v[112:113], v[100:101]
	v_mov_b32_e32 v112, v96
	v_mov_b32_e32 v113, v48
	v_mov_b32_e32 v96, v97
	v_mov_b32_e32 v97, v49
	v_mov_b32_e32 v92, v104
	v_mov_b32_e32 v94, v105
	v_add_f32_e32 v0, v102, v103
	v_pk_add_f32 v[96:97], v[112:113], v[96:97]
	v_pk_add_f32 v[92:93], v[92:93], v[94:95]
	v_pk_mul_f32 v[106:107], v[42:43], v[42:43]
	v_pk_add_f32 v[96:97], v[100:101], v[96:97]
	v_pk_add_f32 v[92:93], v[92:93], v[0:1]
	v_pk_mul_f32 v[102:103], v[44:45], v[44:45]
	v_pk_add_f32 v[92:93], v[96:97], v[92:93]
	v_mov_b32_e32 v94, v106
	v_mov_b32_e32 v95, v42
	v_mov_b32_e32 v96, v107
	v_mov_b32_e32 v97, v43
	v_pk_add_f32 v[94:95], v[94:95], v[96:97]
	v_mov_b32_e32 v96, v102
	v_mov_b32_e32 v97, v44
	v_mov_b32_e32 v100, v103
	v_mov_b32_e32 v101, v45
	v_pk_mul_f32 v[76:77], v[66:67], v[66:67]
	v_pk_add_f32 v[96:97], v[96:97], v[100:101]
	v_pk_mul_f32 v[74:75], v[68:69], v[68:69]
	v_pk_mul_f32 v[82:83], v[58:59], v[58:59]
	v_pk_add_f32 v[94:95], v[94:95], v[96:97]
	v_mov_b32_e32 v96, v76
	v_mov_b32_e32 v97, v58
	v_mov_b32_e32 v76, v77
	v_mov_b32_e32 v77, v59
	v_add_f32_e32 v71, v66, v67
	v_add_f32_e32 v73, v68, v69
	v_pk_mul_f32 v[78:79], v[60:61], v[60:61]
	v_pk_add_f32 v[76:77], v[96:97], v[76:77]
; #define LAS __attribute__((address_space(3)))
; __device__ __forceinline__ unsigned cvt_pk_bf16(float lo, float hi) { unsigned r; asm volatile("v_cvt_pk_bf16_f32 %0, %1, %2" : "=v"(r) : "v"(lo), "v"(hi)); return r; }
; __device__ __forceinline__ void row_pass(const Params& P, int l, int mode, LAS float* pl) {
;     ...
;             wave_sum2(s[0], s[1]); wave_sum2(q[0], q[1]);
; #pragma unroll
;             for (int r = 0; r < 2; ++r) if (ok[r]) { const float mean = s[r] * (1.f / DM); const float var = fmaxf(q[r] * (1.f / DM) - mean * mean, 0.f); const float rstd = 1.f / sqrtf(var + LN_EPS);
;                 const LAS float* mm = pl + 5120 + mv[r] * DM;
; #pragma unroll
;                 for (int j = 0; j < 4; ++j) { const f32x4 sh = *(const LAS f32x4*)(mm + 4 * lane + 256 * j), sc1 = *(const LAS f32x4*)(mm + 3072 + 4 * lane + 256 * j);
;                     const f32x4 hv = (v[r][j] - mean) * rstd * sc1 + sh; u32x2 o; o.x = cvt_pk_bf16(hv[0], hv[1]); o.y = cvt_pk_bf16(hv[2], hv[3]);
;                     *(u32x2*)(H + (size_t)row[r] * DM + 4 * lane + 256 * j) = o; } }
	v_mov_b32_e32 v96, v74
	v_mov_b32_e32 v97, v60
	v_mov_b32_e32 v74, v75
	v_mov_b32_e32 v75, v61
	v_mov_b32_e32 v70, v82
	v_mov_b32_e32 v72, v83
	v_add_f32_e32 v78, v78, v79
	v_pk_add_f32 v[74:75], v[96:97], v[74:75]
	v_pk_add_f32 v[70:71], v[70:71], v[72:73]
	v_mov_b32_e32 v79, v1
	v_pk_mul_f32 v[86:87], v[54:55], v[54:55]
	v_pk_add_f32 v[74:75], v[76:77], v[74:75]
	v_pk_add_f32 v[70:71], v[70:71], v[78:79]
	v_pk_mul_f32 v[84:85], v[56:57], v[56:57]
	v_pk_add_f32 v[70:71], v[74:75], v[70:71]
	v_mov_b32_e32 v72, v86
	v_mov_b32_e32 v73, v54
	v_mov_b32_e32 v74, v87
	v_mov_b32_e32 v75, v55
	v_pk_add_f32 v[72:73], v[72:73], v[74:75]
	v_mov_b32_e32 v74, v84
	v_mov_b32_e32 v75, v56
	v_mov_b32_e32 v76, v85
	v_mov_b32_e32 v77, v57
	v_pk_add_f32 v[74:75], v[74:75], v[76:77]
	v_pk_mul_f32 v[90:91], v[62:63], v[62:63]
	v_pk_add_f32 v[72:73], v[72:73], v[74:75]
	v_pk_mul_f32 v[88:89], v[64:65], v[64:65]
	v_pk_add_f32 v[70:71], v[72:73], v[70:71]
	v_mov_b32_e32 v72, v90
	v_mov_b32_e32 v73, v62
	v_mov_b32_e32 v74, v91
	v_mov_b32_e32 v75, v63
	v_pk_add_f32 v[72:73], v[72:73], v[74:75]
	v_mov_b32_e32 v74, v88
	v_mov_b32_e32 v75, v64
	v_mov_b32_e32 v76, v89
	v_mov_b32_e32 v77, v65
	v_pk_add_f32 v[74:75], v[74:75], v[76:77]
	v_pk_mul_f32 v[108:109], v[40:41], v[40:41]
	v_pk_add_f32 v[72:73], v[72:73], v[74:75]
	v_pk_mul_f32 v[110:111], v[38:39], v[38:39]
	v_pk_add_f32 v[70:71], v[72:73], v[70:71]
	s_nop 1
	v_mov_b32_dpp v73, v71 quad_perm:[1,0,3,2] row_mask:0xf bank_mask:0xf
	s_nop 1
	v_mov_b32_dpp v72, v70 quad_perm:[1,0,3,2] row_mask:0xf bank_mask:0xf
	v_pk_add_f32 v[92:93], v[94:95], v[92:93]
	v_mov_b32_e32 v94, v110
	v_mov_b32_e32 v95, v38
	v_mov_b32_e32 v74, v111
	s_waitcnt lgkmcnt(0)
	v_pk_add_f32 v[70:71], v[70:71], v[72:73]
	s_nop 1
	v_mov_b32_dpp v73, v71 quad_perm:[2,3,0,1] row_mask:0xf bank_mask:0xf
	s_nop 1
	v_mov_b32_dpp v72, v70 quad_perm:[2,3,0,1] row_mask:0xf bank_mask:0xf
	v_mov_b32_e32 v75, v39
	v_mov_b32_e32 v76, v108
	v_mov_b32_e32 v77, v40
	v_mov_b32_e32 v78, v109
	s_waitcnt lgkmcnt(0)
	v_pk_add_f32 v[70:71], v[70:71], v[72:73]
	s_nop 1
	v_mov_b32_dpp v73, v71 row_half_mirror row_mask:0xf bank_mask:0xf
	s_nop 1
	v_mov_b32_dpp v72, v70 row_half_mirror row_mask:0xf bank_mask:0xf
	v_mov_b32_e32 v79, v41
	v_pk_add_f32 v[74:75], v[94:95], v[74:75]
	v_pk_add_f32 v[76:77], v[76:77], v[78:79]
	s_ashr_i32 s21, s20, 31
	s_waitcnt lgkmcnt(0)
	v_pk_add_f32 v[70:71], v[70:71], v[72:73]
	s_nop 1
	v_mov_b32_dpp v73, v71 row_mirror row_mask:0xf bank_mask:0xf
	s_nop 1
	v_mov_b32_dpp v72, v70 row_mirror row_mask:0xf bank_mask:0xf
	v_pk_add_f32 v[74:75], v[74:75], v[76:77]
	s_waitcnt lgkmcnt(0)
	v_pk_add_f32 v[70:71], v[70:71], v[72:73]
	v_pk_add_f32 v[74:75], v[74:75], v[92:93]
	s_nop 1
	v_mov_b32_dpp v77, v75 quad_perm:[1,0,3,2] row_mask:0xf bank_mask:0xf
	s_nop 1
	v_mov_b32_dpp v76, v74 quad_perm:[1,0,3,2] row_mask:0xf bank_mask:0xf
	ds_bpermute_b32 v73, v195, v71
	ds_bpermute_b32 v72, v195, v70
	s_waitcnt lgkmcnt(0)
	v_pk_add_f32 v[74:75], v[74:75], v[76:77]
	s_nop 1
	v_mov_b32_dpp v77, v75 quad_perm:[2,3,0,1] row_mask:0xf bank_mask:0xf
	s_nop 1
	v_mov_b32_dpp v76, v74 quad_perm:[2,3,0,1] row_mask:0xf bank_mask:0xf
	s_waitcnt lgkmcnt(0)
	v_pk_add_f32 v[70:71], v[70:71], v[72:73]
	ds_bpermute_b32 v73, v196, v71
	ds_bpermute_b32 v72, v196, v70
	s_waitcnt lgkmcnt(0)
	v_pk_add_f32 v[74:75], v[74:75], v[76:77]
	s_nop 1
	v_mov_b32_dpp v77, v75 row_half_mirror row_mask:0xf bank_mask:0xf
	s_nop 1
	v_mov_b32_dpp v76, v74 row_half_mirror row_mask:0xf bank_mask:0xf
	s_waitcnt lgkmcnt(0)
	v_pk_add_f32 v[70:71], v[70:71], v[72:73]
	s_waitcnt lgkmcnt(0)
	v_pk_add_f32 v[74:75], v[74:75], v[76:77]
	v_pk_mul_f32 v[78:79], v[70:71], s[2:3] op_sel_hi:[1,0]
	s_nop 1
	v_mov_b32_dpp v77, v75 row_mirror row_mask:0xf bank_mask:0xf
	v_fma_f32 v0, -v79, v79, v78
	v_max_f32_e32 v0, 0, v0
	v_add_f32_e32 v0, 0x358637bd, v0
	v_mul_f32_e32 v70, 0x4f800000, v0
	v_cmp_gt_f32_e32 vcc, s69, v0
	s_nop 1
	v_mov_b32_dpp v76, v74 row_mirror row_mask:0xf bank_mask:0xf
	v_sub_f32_e32 v67, v67, v79
	v_cndmask_b32_e32 v0, v0, v70, vcc
	v_sqrt_f32_e32 v78, v0
	v_sub_f32_e32 v66, v66, v79
	s_waitcnt lgkmcnt(0)
	v_pk_add_f32 v[70:71], v[74:75], v[76:77]
	v_sub_f32_e32 v69, v69, v79
	v_add_u32_e32 v74, -1, v78
	v_fma_f32 v75, -v74, v78, v0
	v_cmp_ge_f32_e64 s[0:1], 0, v75
	v_add_u32_e32 v75, 1, v78
	v_fma_f32 v76, -v75, v78, v0
	v_cndmask_b32_e64 v74, v78, v74, s[0:1]
	v_cmp_lt_f32_e64 s[0:1], 0, v76
	v_sub_f32_e32 v68, v68, v79
	v_sub_f32_e32 v59, v59, v79
	v_cndmask_b32_e64 v74, v74, v75, s[0:1]
	v_mul_f32_e32 v75, 0x37800000, v74
	v_cndmask_b32_e32 v74, v74, v75, vcc
	v_cmp_class_f32_e32 vcc, v0, v217
	v_sub_f32_e32 v58, v58, v79
	v_sub_f32_e32 v61, v61, v79
	v_cndmask_b32_e32 v0, v74, v0, vcc
	v_div_scale_f32 v74, s[0:1], v0, v0, 1.0
	v_rcp_f32_e32 v75, v74
	s_lshl_b64 s[0:1], s[20:21], 11
	v_sub_f32_e32 v60, v60, v79
	ds_bpermute_b32 v73, v195, v71
	v_fma_f32 v76, -v74, v75, 1.0
	v_fmac_f32_e32 v75, v76, v75
	v_div_scale_f32 v76, vcc, 1.0, v0, 1.0
	v_mul_f32_e32 v77, v76, v75
	v_fma_f32 v78, -v74, v77, v76
	v_fmac_f32_e32 v77, v78, v75
	v_fma_f32 v74, -v74, v77, v76
	v_div_fmas_f32 v74, v74, v75, v77
	v_div_fixup_f32 v0, v74, v0, 1.0
	ds_read_b128 v[74:77], v98 offset:20480
	ds_read_b128 v[82:85], v98 offset:32768
	v_pk_mul_f32 v[66:67], v[66:67], v[0:1] op_sel_hi:[1,0]
	v_pk_mul_f32 v[68:69], v[68:69], v[0:1] op_sel_hi:[1,0]
	v_pk_mul_f32 v[58:59], v[58:59], v[0:1] op_sel_hi:[1,0]
	v_pk_mul_f32 v[60:61], v[60:61], v[0:1] op_sel_hi:[1,0]
	s_waitcnt lgkmcnt(0)
; #define LAS __attribute__((address_space(3)))
; __device__ __forceinline__ unsigned cvt_pk_bf16(float lo, float hi) { unsigned r; asm volatile("v_cvt_pk_bf16_f32 %0, %1, %2" : "=v"(r) : "v"(lo), "v"(hi)); return r; }
; __device__ __forceinline__ void row_pass(const Params& P, int l, int mode, LAS float* pl) {
;     ...
;             for (int r = 0; r < 2; ++r) if (ok[r]) { const float mean = s[r] * (1.f / DM); const float var = fmaxf(q[r] * (1.f / DM) - mean * mean, 0.f); const float rstd = 1.f / sqrtf(var + LN_EPS);
;                 const LAS float* mm = pl + 5120 + mv[r] * DM;
; #pragma unroll
;                 for (int j = 0; j < 4; ++j) { const f32x4 sh = *(const LAS f32x4*)(mm + 4 * lane + 256 * j), sc1 = *(const LAS f32x4*)(mm + 3072 + 4 * lane + 256 * j);
;                     const f32x4 hv = (v[r][j] - mean) * rstd * sc1 + sh; u32x2 o; o.x = cvt_pk_bf16(hv[0], hv[1]); o.y = cvt_pk_bf16(hv[2], hv[3]);
;                     *(u32x2*)(H + (size_t)row[r] * DM + 4 * lane + 256 * j) = o; } }
	v_pk_fma_f32 v[66:67], v[82:83], v[66:67], v[74:75]
	v_lshl_add_u64 v[82:83], v[146:147], 0, s[0:1]
	v_pk_fma_f32 v[68:69], v[84:85], v[68:69], v[76:77]
	v_cvt_pk_bf16_f32 v66, v66, v67
	ds_bpermute_b32 v72, v195, v70
	v_cvt_pk_bf16_f32 v67, v68, v69
	global_store_dwordx2 v[82:83], v[66:67], off
	ds_read_b128 v[66:69], v98 offset:21504
	ds_read_b128 v[74:77], v98 offset:33792
	v_sub_f32_e32 v55, v55, v79
	v_sub_f32_e32 v54, v54, v79
	v_sub_f32_e32 v57, v57, v79
	v_sub_f32_e32 v56, v56, v79
	s_waitcnt lgkmcnt(0)
	v_pk_fma_f32 v[58:59], v[74:75], v[58:59], v[66:67]
	v_pk_fma_f32 v[60:61], v[76:77], v[60:61], v[68:69]
	v_cvt_pk_bf16_f32 v58, v58, v59
	v_pk_mul_f32 v[54:55], v[54:55], v[0:1] op_sel_hi:[1,0]
	v_cvt_pk_bf16_f32 v59, v60, v61
	global_store_dwordx2 v[82:83], v[58:59], off offset:512
	ds_read_b128 v[58:61], v98 offset:22528
	ds_read_b128 v[66:69], v98 offset:34816
	v_pk_mul_f32 v[56:57], v[56:57], v[0:1] op_sel_hi:[1,0]
	v_pk_add_f32 v[70:71], v[70:71], v[72:73]
	ds_bpermute_b32 v73, v196, v71
	ds_bpermute_b32 v72, v196, v70
	s_waitcnt lgkmcnt(2)
	v_pk_fma_f32 v[54:55], v[54:55], v[66:67], v[58:59]
	v_pk_fma_f32 v[56:57], v[56:57], v[68:69], v[60:61]
	v_cvt_pk_bf16_f32 v54, v54, v55
	v_sub_f32_e32 v63, v63, v79
	v_cvt_pk_bf16_f32 v55, v56, v57
	global_store_dwordx2 v[82:83], v[54:55], off offset:1024
	ds_read_b128 v[54:57], v98 offset:23552
	ds_read_b128 v[58:61], v98 offset:35840
	v_sub_f32_e32 v62, v62, v79
	v_sub_f32_e32 v65, v65, v79
	v_sub_f32_e32 v64, v64, v79
	v_pk_mul_f32 v[62:63], v[62:63], v[0:1] op_sel_hi:[1,0]
	v_pk_mul_f32 v[64:65], v[64:65], v[0:1] op_sel_hi:[1,0]
	s_waitcnt lgkmcnt(0)
	v_pk_fma_f32 v[54:55], v[62:63], v[58:59], v[54:55]
	s_and_b64 vcc, exec, s[10:11]
	v_pk_fma_f32 v[56:57], v[64:65], v[60:61], v[56:57]
	v_cvt_pk_bf16_f32 v54, v54, v55
	s_nop 0
	v_cvt_pk_bf16_f32 v55, v56, v57
	global_store_dwordx2 v[82:83], v[54:55], off offset:1536
	s_cbranch_vccnz .LBB0_1310
	v_pk_add_f32 v[54:55], v[70:71], v[72:73]
	s_ashr_i32 s19, s18, 31
	v_pk_mul_f32 v[62:63], v[54:55], s[2:3] op_sel_hi:[1,0]
	s_nop 0
	v_fma_f32 v0, -v63, v63, v62
	v_max_f32_e32 v0, 0, v0
	v_add_f32_e32 v0, 0x358637bd, v0
	v_mul_f32_e32 v54, 0x4f800000, v0
	v_cmp_gt_f32_e32 vcc, s69, v0
	v_sub_f32_e32 v51, v51, v63
	v_sub_f32_e32 v50, v50, v63
	v_cndmask_b32_e32 v0, v0, v54, vcc
	v_sqrt_f32_e32 v54, v0
	v_sub_f32_e32 v53, v53, v63
	v_sub_f32_e32 v52, v52, v63
	v_sub_f32_e32 v47, v47, v63
	v_add_u32_e32 v55, -1, v54
	v_fma_f32 v57, -v55, v54, v0
	v_add_u32_e32 v56, 1, v54
	v_cmp_ge_f32_e64 s[0:1], 0, v57
	v_sub_f32_e32 v46, v46, v63
	v_sub_f32_e32 v49, v49, v63
	v_cndmask_b32_e64 v55, v54, v55, s[0:1]
	v_fma_f32 v54, -v56, v54, v0
	v_cmp_lt_f32_e64 s[0:1], 0, v54
	v_sub_f32_e32 v48, v48, v63
	v_sub_f32_e32 v43, v43, v63
	v_cndmask_b32_e64 v54, v55, v56, s[0:1]
	v_mul_f32_e32 v55, 0x37800000, v54
	v_cndmask_b32_e32 v54, v54, v55, vcc
	v_cmp_class_f32_e32 vcc, v0, v217
	v_sub_f32_e32 v42, v42, v63
	v_sub_f32_e32 v45, v45, v63
	v_cndmask_b32_e32 v0, v54, v0, vcc
	v_div_scale_f32 v54, s[0:1], v0, v0, 1.0
	v_rcp_f32_e32 v55, v54
	s_lshl_b64 s[0:1], s[18:19], 11
	v_sub_f32_e32 v44, v44, v63
	v_sub_f32_e32 v39, v39, v63
	v_fma_f32 v56, -v54, v55, 1.0
	v_fmac_f32_e32 v55, v56, v55
	v_div_scale_f32 v56, vcc, 1.0, v0, 1.0
	v_mul_f32_e32 v57, v56, v55
	v_fma_f32 v58, -v54, v57, v56
	v_fmac_f32_e32 v57, v58, v55
	v_fma_f32 v54, -v54, v57, v56
	v_div_fmas_f32 v54, v54, v55, v57
	v_div_fixup_f32 v0, v54, v0, 1.0
	ds_read_b128 v[54:57], v80 offset:20480
	ds_read_b128 v[58:61], v80 offset:32768
	v_pk_mul_f32 v[50:51], v[50:51], v[0:1] op_sel_hi:[1,0]
	v_pk_mul_f32 v[52:53], v[52:53], v[0:1] op_sel_hi:[1,0]
	v_pk_mul_f32 v[46:47], v[46:47], v[0:1] op_sel_hi:[1,0]
	v_pk_mul_f32 v[48:49], v[48:49], v[0:1] op_sel_hi:[1,0]
	s_waitcnt lgkmcnt(0)
	v_pk_fma_f32 v[50:51], v[50:51], v[58:59], v[54:55]
	v_lshl_add_u64 v[58:59], v[146:147], 0, s[0:1]
	v_pk_fma_f32 v[52:53], v[52:53], v[60:61], v[56:57]
	v_cvt_pk_bf16_f32 v50, v50, v51
	v_pk_mul_f32 v[42:43], v[42:43], v[0:1] op_sel_hi:[1,0]
	v_cvt_pk_bf16_f32 v51, v52, v53
	global_store_dwordx2 v[58:59], v[50:51], off
	ds_read_b128 v[50:53], v80 offset:21504
	ds_read_b128 v[54:57], v80 offset:33792
	v_pk_mul_f32 v[44:45], v[44:45], v[0:1] op_sel_hi:[1,0]
	v_sub_f32_e32 v38, v38, v63
	v_sub_f32_e32 v41, v41, v63
	v_sub_f32_e32 v40, v40, v63
	s_waitcnt lgkmcnt(0)
	v_pk_fma_f32 v[46:47], v[46:47], v[54:55], v[50:51]
	v_pk_fma_f32 v[48:49], v[48:49], v[56:57], v[52:53]
	v_cvt_pk_bf16_f32 v46, v46, v47
	v_pk_mul_f32 v[38:39], v[38:39], v[0:1] op_sel_hi:[1,0]
	v_cvt_pk_bf16_f32 v47, v48, v49
	global_store_dwordx2 v[58:59], v[46:47], off offset:512
	ds_read_b128 v[46:49], v80 offset:22528
	ds_read_b128 v[50:53], v80 offset:34816
	v_pk_mul_f32 v[40:41], v[40:41], v[0:1] op_sel_hi:[1,0]
	s_waitcnt lgkmcnt(0)
	v_pk_fma_f32 v[42:43], v[42:43], v[50:51], v[46:47]
	v_pk_fma_f32 v[44:45], v[44:45], v[52:53], v[48:49]
	v_cvt_pk_bf16_f32 v42, v42, v43
	s_nop 0
	v_cvt_pk_bf16_f32 v43, v44, v45
	global_store_dwordx2 v[58:59], v[42:43], off offset:1024
	ds_read_b128 v[42:45], v80 offset:23552
	ds_read_b128 v[46:49], v80 offset:35840
	s_waitcnt lgkmcnt(0)
	v_pk_fma_f32 v[38:39], v[38:39], v[46:47], v[42:43]
	v_pk_fma_f32 v[40:41], v[40:41], v[48:49], v[44:45]
	v_cvt_pk_bf16_f32 v38, v38, v39
	s_nop 0
	v_cvt_pk_bf16_f32 v39, v40, v41
	global_store_dwordx2 v[58:59], v[38:39], off offset:1536
